# RWKV scan consumer: q products accumulated in one chain (one instruction fewer per token)
# speedup vs baseline: 1.0091x; 1.0061x over previous
.LBB0_1750:
	s_and_b32 s23, s22, 1
	s_mul_i32 s2, s23, 0xc000
	s_add_i32 s2, s2, 0
	v_add_u32_e32 v20, s2, v10
	s_add_i32 s2, s2, s5
	v_lshl_add_u32 v21, v1, 2, s2
	ds_read_b128 v[36:39], v20 offset:0
	ds_read_b128 v[40:43], v20 offset:8192
	ds_read_b64 v[56:57], v21 offset:40960
	ds_read_b128 v[48:51], v20 offset:24576
	ds_read_b128 v[44:47], v20 offset:16384
	ds_read_b128 v[52:55], v20 offset:32768
	s_waitcnt lgkmcnt(0)
	v_pk_mul_f32 v[22:23], v[2:3], v[36:37] op_sel:[0,0] op_sel_hi:[1,0]
	ds_read_b128 v[60:63], v20 offset:256
	v_pk_fma_f32 v[22:23], v[4:5], v[36:37], v[22:23] op_sel:[0,1,0] op_sel_hi:[1,1,1]
	ds_read_b128 v[64:67], v20 offset:8448
	v_pk_fma_f32 v[22:23], v[6:7], v[38:39], v[22:23] op_sel:[0,0,0] op_sel_hi:[1,0,1]
	ds_read_b64 v[80:81], v21 offset:41216
	v_pk_fma_f32 v[22:23], v[8:9], v[38:39], v[22:23] op_sel:[0,1,0] op_sel_hi:[1,1,1]
	ds_read_b128 v[72:75], v20 offset:24832
	ds_read_b128 v[68:71], v20 offset:16640
	ds_read_b128 v[76:79], v20 offset:33024
	v_add_f32_dpp v22, v22, v22 quad_perm:[1,0,3,2] row_mask:0xf bank_mask:0xf
	v_add_f32_dpp v23, v23, v23 quad_perm:[1,0,3,2] row_mask:0xf bank_mask:0xf
	v_pk_mul_f32 v[84:85], v[2:3], v[40:41] op_sel:[0,0] op_sel_hi:[1,0]
	v_pk_mul_f32 v[86:87], v[4:5], v[40:41] op_sel:[0,1] op_sel_hi:[1,1]
	v_add_f32_dpp v22, v22, v22 quad_perm:[2,3,0,1] row_mask:0xf bank_mask:0xf
	v_add_f32_dpp v23, v23, v23 quad_perm:[2,3,0,1] row_mask:0xf bank_mask:0xf
	v_pk_mul_f32 v[88:89], v[6:7], v[42:43] op_sel:[0,0] op_sel_hi:[1,0]
	v_pk_mul_f32 v[90:91], v[8:9], v[42:43] op_sel:[0,1] op_sel_hi:[1,1]
	v_add_f32_dpp v22, v22, v22 row_half_mirror row_mask:0xf bank_mask:0xf
	v_add_f32_dpp v23, v23, v23 row_half_mirror row_mask:0xf bank_mask:0xf
	v_pk_fma_f32 v[84:85], v[48:49], v[56:57], v[84:85] op_sel:[0,0,0] op_sel_hi:[0,1,1]
	v_pk_fma_f32 v[86:87], v[48:49], v[56:57], v[86:87] op_sel:[1,0,0] op_sel_hi:[1,1,1]
	v_add_f32_dpp v22, v22, v22 row_mirror row_mask:0xf bank_mask:0xf
	v_add_f32_dpp v23, v23, v23 row_mirror row_mask:0xf bank_mask:0xf
	v_pk_fma_f32 v[88:89], v[50:51], v[56:57], v[88:89] op_sel:[0,0,0] op_sel_hi:[0,1,1]
	v_pk_fma_f32 v[90:91], v[50:51], v[56:57], v[90:91] op_sel:[1,0,0] op_sel_hi:[1,1,1]
	v_pk_fma_f32 v[2:3], v[44:45], v[22:23], v[84:85] op_sel:[0,0,0] op_sel_hi:[0,1,1] neg_lo:[1,0,0] neg_hi:[1,0,0]
	v_pk_fma_f32 v[4:5], v[44:45], v[22:23], v[86:87] op_sel:[1,0,0] op_sel_hi:[1,1,1] neg_lo:[1,0,0] neg_hi:[1,0,0]
	v_pk_fma_f32 v[6:7], v[46:47], v[22:23], v[88:89] op_sel:[0,0,0] op_sel_hi:[0,1,1] neg_lo:[1,0,0] neg_hi:[1,0,0]
	v_pk_fma_f32 v[8:9], v[46:47], v[22:23], v[90:91] op_sel:[1,0,0] op_sel_hi:[1,1,1] neg_lo:[1,0,0] neg_hi:[1,0,0]
	s_waitcnt lgkmcnt(0)
	v_pk_mul_f32 v[22:23], v[2:3], v[60:61] op_sel:[0,0] op_sel_hi:[1,0]
	v_pk_mul_f32 v[24:25], v[2:3], v[52:53] op_sel:[0,0] op_sel_hi:[1,0]
	ds_read_b128 v[36:39], v20 offset:512
	v_pk_fma_f32 v[22:23], v[4:5], v[60:61], v[22:23] op_sel:[0,1,0] op_sel_hi:[1,1,1]
	v_pk_fma_f32 v[24:25], v[4:5], v[52:53], v[24:25] op_sel:[0,1,0] op_sel_hi:[1,1,1]
	ds_read_b128 v[40:43], v20 offset:8704
	v_pk_fma_f32 v[22:23], v[6:7], v[62:63], v[22:23] op_sel:[0,0,0] op_sel_hi:[1,0,1]
	v_pk_fma_f32 v[24:25], v[6:7], v[54:55], v[24:25] op_sel:[0,0,0] op_sel_hi:[1,0,1]
	ds_read_b64 v[56:57], v21 offset:41472
	v_pk_fma_f32 v[22:23], v[8:9], v[62:63], v[22:23] op_sel:[0,1,0] op_sel_hi:[1,1,1]
	v_pk_fma_f32 v[24:25], v[8:9], v[54:55], v[24:25] op_sel:[0,1,0] op_sel_hi:[1,1,1]
	ds_read_b128 v[48:51], v20 offset:25088
	ds_read_b128 v[44:47], v20 offset:16896
	ds_read_b128 v[52:55], v20 offset:33280
	v_add_f32_dpp v22, v22, v22 quad_perm:[1,0,3,2] row_mask:0xf bank_mask:0xf
	v_add_f32_dpp v23, v23, v23 quad_perm:[1,0,3,2] row_mask:0xf bank_mask:0xf
	v_pk_mul_f32 v[84:85], v[2:3], v[64:65] op_sel:[0,0] op_sel_hi:[1,0]
	v_pk_mul_f32 v[86:87], v[4:5], v[64:65] op_sel:[0,1] op_sel_hi:[1,1]
	v_add_f32_dpp v22, v22, v22 quad_perm:[2,3,0,1] row_mask:0xf bank_mask:0xf
	v_add_f32_dpp v23, v23, v23 quad_perm:[2,3,0,1] row_mask:0xf bank_mask:0xf
	v_pk_mul_f32 v[88:89], v[6:7], v[66:67] op_sel:[0,0] op_sel_hi:[1,0]
	v_pk_mul_f32 v[90:91], v[8:9], v[66:67] op_sel:[0,1] op_sel_hi:[1,1]
	v_add_f32_dpp v22, v22, v22 row_half_mirror row_mask:0xf bank_mask:0xf
	v_add_f32_dpp v23, v23, v23 row_half_mirror row_mask:0xf bank_mask:0xf
	v_pk_fma_f32 v[84:85], v[72:73], v[80:81], v[84:85] op_sel:[0,0,0] op_sel_hi:[0,1,1]
	v_pk_fma_f32 v[86:87], v[72:73], v[80:81], v[86:87] op_sel:[1,0,0] op_sel_hi:[1,1,1]
	v_add_f32_dpp v22, v22, v22 row_mirror row_mask:0xf bank_mask:0xf
	v_add_f32_dpp v23, v23, v23 row_mirror row_mask:0xf bank_mask:0xf
	v_pk_fma_f32 v[88:89], v[74:75], v[80:81], v[88:89] op_sel:[0,0,0] op_sel_hi:[0,1,1]
	v_pk_fma_f32 v[90:91], v[74:75], v[80:81], v[90:91] op_sel:[1,0,0] op_sel_hi:[1,1,1]
	v_pk_fma_f32 v[2:3], v[68:69], v[22:23], v[84:85] op_sel:[0,0,0] op_sel_hi:[0,1,1] neg_lo:[1,0,0] neg_hi:[1,0,0]
	v_pk_fma_f32 v[4:5], v[68:69], v[22:23], v[86:87] op_sel:[1,0,0] op_sel_hi:[1,1,1] neg_lo:[1,0,0] neg_hi:[1,0,0]
	v_pk_fma_f32 v[6:7], v[70:71], v[22:23], v[88:89] op_sel:[0,0,0] op_sel_hi:[0,1,1] neg_lo:[1,0,0] neg_hi:[1,0,0]
	v_pk_fma_f32 v[8:9], v[70:71], v[22:23], v[90:91] op_sel:[1,0,0] op_sel_hi:[1,1,1] neg_lo:[1,0,0] neg_hi:[1,0,0]
	s_waitcnt lgkmcnt(0)
	v_pk_mul_f32 v[22:23], v[2:3], v[36:37] op_sel:[0,0] op_sel_hi:[1,0]
	v_pk_mul_f32 v[26:27], v[2:3], v[76:77] op_sel:[0,0] op_sel_hi:[1,0]
	ds_read_b128 v[60:63], v20 offset:768
	v_pk_fma_f32 v[22:23], v[4:5], v[36:37], v[22:23] op_sel:[0,1,0] op_sel_hi:[1,1,1]
	v_pk_fma_f32 v[26:27], v[4:5], v[76:77], v[26:27] op_sel:[0,1,0] op_sel_hi:[1,1,1]
	ds_read_b128 v[64:67], v20 offset:8960
	v_pk_fma_f32 v[22:23], v[6:7], v[38:39], v[22:23] op_sel:[0,0,0] op_sel_hi:[1,0,1]
	v_pk_fma_f32 v[26:27], v[6:7], v[78:79], v[26:27] op_sel:[0,0,0] op_sel_hi:[1,0,1]
	ds_read_b64 v[80:81], v21 offset:41728
	v_pk_fma_f32 v[22:23], v[8:9], v[38:39], v[22:23] op_sel:[0,1,0] op_sel_hi:[1,1,1]
	v_pk_fma_f32 v[26:27], v[8:9], v[78:79], v[26:27] op_sel:[0,1,0] op_sel_hi:[1,1,1]
	ds_read_b128 v[72:75], v20 offset:25344
	ds_read_b128 v[68:71], v20 offset:17152
	ds_read_b128 v[76:79], v20 offset:33536
	v_add_f32_dpp v22, v22, v22 quad_perm:[1,0,3,2] row_mask:0xf bank_mask:0xf
	v_add_f32_dpp v23, v23, v23 quad_perm:[1,0,3,2] row_mask:0xf bank_mask:0xf
	v_pk_mul_f32 v[84:85], v[2:3], v[40:41] op_sel:[0,0] op_sel_hi:[1,0]
	v_pk_mul_f32 v[86:87], v[4:5], v[40:41] op_sel:[0,1] op_sel_hi:[1,1]
	v_add_f32_dpp v22, v22, v22 quad_perm:[2,3,0,1] row_mask:0xf bank_mask:0xf
	v_add_f32_dpp v23, v23, v23 quad_perm:[2,3,0,1] row_mask:0xf bank_mask:0xf
	v_pk_mul_f32 v[88:89], v[6:7], v[42:43] op_sel:[0,0] op_sel_hi:[1,0]
	v_pk_mul_f32 v[90:91], v[8:9], v[42:43] op_sel:[0,1] op_sel_hi:[1,1]
	v_add_f32_dpp v22, v22, v22 row_half_mirror row_mask:0xf bank_mask:0xf
	v_add_f32_dpp v23, v23, v23 row_half_mirror row_mask:0xf bank_mask:0xf
	v_pk_fma_f32 v[84:85], v[48:49], v[56:57], v[84:85] op_sel:[0,0,0] op_sel_hi:[0,1,1]
	v_pk_fma_f32 v[86:87], v[48:49], v[56:57], v[86:87] op_sel:[1,0,0] op_sel_hi:[1,1,1]
	v_add_f32_dpp v22, v22, v22 row_mirror row_mask:0xf bank_mask:0xf
	v_add_f32_dpp v23, v23, v23 row_mirror row_mask:0xf bank_mask:0xf
	v_pk_fma_f32 v[88:89], v[50:51], v[56:57], v[88:89] op_sel:[0,0,0] op_sel_hi:[0,1,1]
	v_pk_fma_f32 v[90:91], v[50:51], v[56:57], v[90:91] op_sel:[1,0,0] op_sel_hi:[1,1,1]
	v_pk_fma_f32 v[2:3], v[44:45], v[22:23], v[84:85] op_sel:[0,0,0] op_sel_hi:[0,1,1] neg_lo:[1,0,0] neg_hi:[1,0,0]
	v_pk_fma_f32 v[4:5], v[44:45], v[22:23], v[86:87] op_sel:[1,0,0] op_sel_hi:[1,1,1] neg_lo:[1,0,0] neg_hi:[1,0,0]
	v_pk_fma_f32 v[6:7], v[46:47], v[22:23], v[88:89] op_sel:[0,0,0] op_sel_hi:[0,1,1] neg_lo:[1,0,0] neg_hi:[1,0,0]
	v_pk_fma_f32 v[8:9], v[46:47], v[22:23], v[90:91] op_sel:[1,0,0] op_sel_hi:[1,1,1] neg_lo:[1,0,0] neg_hi:[1,0,0]
	s_waitcnt lgkmcnt(0)
	v_pk_mul_f32 v[22:23], v[2:3], v[60:61] op_sel:[0,0] op_sel_hi:[1,0]
	v_pk_mul_f32 v[28:29], v[2:3], v[52:53] op_sel:[0,0] op_sel_hi:[1,0]
	ds_read_b128 v[36:39], v20 offset:1024
	v_pk_fma_f32 v[22:23], v[4:5], v[60:61], v[22:23] op_sel:[0,1,0] op_sel_hi:[1,1,1]
	v_pk_fma_f32 v[28:29], v[4:5], v[52:53], v[28:29] op_sel:[0,1,0] op_sel_hi:[1,1,1]
	ds_read_b128 v[40:43], v20 offset:9216
	v_pk_fma_f32 v[22:23], v[6:7], v[62:63], v[22:23] op_sel:[0,0,0] op_sel_hi:[1,0,1]
	v_pk_fma_f32 v[28:29], v[6:7], v[54:55], v[28:29] op_sel:[0,0,0] op_sel_hi:[1,0,1]
	ds_read_b64 v[56:57], v21 offset:41984
	v_pk_fma_f32 v[22:23], v[8:9], v[62:63], v[22:23] op_sel:[0,1,0] op_sel_hi:[1,1,1]
	v_pk_fma_f32 v[28:29], v[8:9], v[54:55], v[28:29] op_sel:[0,1,0] op_sel_hi:[1,1,1]
	ds_read_b128 v[48:51], v20 offset:25600
	ds_read_b128 v[44:47], v20 offset:17408
	ds_read_b128 v[52:55], v20 offset:33792
	v_add_f32_dpp v24, v24, v24 row_ror:12 row_mask:0xf bank_mask:0x5
	v_add_f32_dpp v25, v25, v25 row_ror:4 row_mask:0xf bank_mask:0xa
	v_add_f32_dpp v22, v22, v22 quad_perm:[1,0,3,2] row_mask:0xf bank_mask:0xf
	v_add_f32_dpp v23, v23, v23 quad_perm:[1,0,3,2] row_mask:0xf bank_mask:0xf
	v_pk_mul_f32 v[84:85], v[2:3], v[64:65] op_sel:[0,0] op_sel_hi:[1,0]
	v_pk_mul_f32 v[86:87], v[4:5], v[64:65] op_sel:[0,1] op_sel_hi:[1,1]
	v_add_f32_dpp v26, v26, v26 row_ror:12 row_mask:0xf bank_mask:0x5
	v_add_f32_dpp v22, v22, v22 quad_perm:[2,3,0,1] row_mask:0xf bank_mask:0xf
	v_add_f32_dpp v23, v23, v23 quad_perm:[2,3,0,1] row_mask:0xf bank_mask:0xf
	v_pk_mul_f32 v[88:89], v[6:7], v[66:67] op_sel:[0,0] op_sel_hi:[1,0]
	v_pk_mul_f32 v[90:91], v[8:9], v[66:67] op_sel:[0,1] op_sel_hi:[1,1]
	v_add_f32_dpp v27, v27, v27 row_ror:4 row_mask:0xf bank_mask:0xa
	v_add_f32_dpp v22, v22, v22 row_half_mirror row_mask:0xf bank_mask:0xf
	v_add_f32_dpp v23, v23, v23 row_half_mirror row_mask:0xf bank_mask:0xf
	v_pk_fma_f32 v[84:85], v[72:73], v[80:81], v[84:85] op_sel:[0,0,0] op_sel_hi:[0,1,1]
	v_pk_fma_f32 v[86:87], v[72:73], v[80:81], v[86:87] op_sel:[1,0,0] op_sel_hi:[1,1,1]
	v_mov_b32_dpp v24, v25 quad_perm:[0,1,2,3] row_mask:0xf bank_mask:0xa
	v_add_f32_dpp v22, v22, v22 row_mirror row_mask:0xf bank_mask:0xf
	v_add_f32_dpp v23, v23, v23 row_mirror row_mask:0xf bank_mask:0xf
	v_pk_fma_f32 v[88:89], v[74:75], v[80:81], v[88:89] op_sel:[0,0,0] op_sel_hi:[0,1,1]
	v_pk_fma_f32 v[90:91], v[74:75], v[80:81], v[90:91] op_sel:[1,0,0] op_sel_hi:[1,1,1]
	v_mov_b32_dpp v26, v27 quad_perm:[0,1,2,3] row_mask:0xf bank_mask:0xa
	v_pk_fma_f32 v[2:3], v[68:69], v[22:23], v[84:85] op_sel:[0,0,0] op_sel_hi:[0,1,1] neg_lo:[1,0,0] neg_hi:[1,0,0]
	v_pk_fma_f32 v[4:5], v[68:69], v[22:23], v[86:87] op_sel:[1,0,0] op_sel_hi:[1,1,1] neg_lo:[1,0,0] neg_hi:[1,0,0]
	v_pk_fma_f32 v[6:7], v[70:71], v[22:23], v[88:89] op_sel:[0,0,0] op_sel_hi:[0,1,1] neg_lo:[1,0,0] neg_hi:[1,0,0]
	v_pk_fma_f32 v[8:9], v[70:71], v[22:23], v[90:91] op_sel:[1,0,0] op_sel_hi:[1,1,1] neg_lo:[1,0,0] neg_hi:[1,0,0]
	s_waitcnt lgkmcnt(0)
	v_pk_mul_f32 v[22:23], v[2:3], v[36:37] op_sel:[0,0] op_sel_hi:[1,0]
	v_pk_mul_f32 v[58:59], v[2:3], v[76:77] op_sel:[0,0] op_sel_hi:[1,0]
	ds_read_b128 v[60:63], v20 offset:1280
	v_pk_fma_f32 v[22:23], v[4:5], v[36:37], v[22:23] op_sel:[0,1,0] op_sel_hi:[1,1,1]
	v_pk_fma_f32 v[58:59], v[4:5], v[76:77], v[58:59] op_sel:[0,1,0] op_sel_hi:[1,1,1]
	ds_read_b128 v[64:67], v20 offset:9472
	v_pk_fma_f32 v[22:23], v[6:7], v[38:39], v[22:23] op_sel:[0,0,0] op_sel_hi:[1,0,1]
	v_pk_fma_f32 v[58:59], v[6:7], v[78:79], v[58:59] op_sel:[0,0,0] op_sel_hi:[1,0,1]
	ds_read_b64 v[80:81], v21 offset:42240
	v_pk_fma_f32 v[22:23], v[8:9], v[38:39], v[22:23] op_sel:[0,1,0] op_sel_hi:[1,1,1]
	v_pk_fma_f32 v[58:59], v[8:9], v[78:79], v[58:59] op_sel:[0,1,0] op_sel_hi:[1,1,1]
	ds_read_b128 v[72:75], v20 offset:25856
	ds_read_b128 v[68:71], v20 offset:17664
	ds_read_b128 v[76:79], v20 offset:34048
	v_add_f32_dpp v24, v24, v24 row_ror:8 row_mask:0xf bank_mask:0x3
	v_add_f32_dpp v26, v26, v26 row_ror:8 row_mask:0xf bank_mask:0xc
	v_add_f32_dpp v22, v22, v22 quad_perm:[1,0,3,2] row_mask:0xf bank_mask:0xf
	v_add_f32_dpp v23, v23, v23 quad_perm:[1,0,3,2] row_mask:0xf bank_mask:0xf
	v_pk_mul_f32 v[84:85], v[2:3], v[40:41] op_sel:[0,0] op_sel_hi:[1,0]
	v_pk_mul_f32 v[86:87], v[4:5], v[40:41] op_sel:[0,1] op_sel_hi:[1,1]
	v_mov_b32_dpp v24, v26 quad_perm:[0,1,2,3] row_mask:0xf bank_mask:0xc
	v_add_f32_dpp v22, v22, v22 quad_perm:[2,3,0,1] row_mask:0xf bank_mask:0xf
	v_add_f32_dpp v23, v23, v23 quad_perm:[2,3,0,1] row_mask:0xf bank_mask:0xf
	v_pk_mul_f32 v[88:89], v[6:7], v[42:43] op_sel:[0,0] op_sel_hi:[1,0]
	v_pk_mul_f32 v[90:91], v[8:9], v[42:43] op_sel:[0,1] op_sel_hi:[1,1]
	v_add_f32_dpp v24, v24, v24 quad_perm:[1,0,3,2] row_mask:0xf bank_mask:0xf
	v_add_f32_dpp v22, v22, v22 row_half_mirror row_mask:0xf bank_mask:0xf
	v_add_f32_dpp v23, v23, v23 row_half_mirror row_mask:0xf bank_mask:0xf
	v_pk_fma_f32 v[84:85], v[48:49], v[56:57], v[84:85] op_sel:[0,0,0] op_sel_hi:[0,1,1]
	v_pk_fma_f32 v[86:87], v[48:49], v[56:57], v[86:87] op_sel:[1,0,0] op_sel_hi:[1,1,1]
	v_add_f32_dpp v24, v24, v24 quad_perm:[2,3,0,1] row_mask:0xf bank_mask:0xf
	v_add_f32_dpp v22, v22, v22 row_mirror row_mask:0xf bank_mask:0xf
	v_add_f32_dpp v23, v23, v23 row_mirror row_mask:0xf bank_mask:0xf
	v_pk_fma_f32 v[88:89], v[50:51], v[56:57], v[88:89] op_sel:[0,0,0] op_sel_hi:[0,1,1]
	v_pk_fma_f32 v[90:91], v[50:51], v[56:57], v[90:91] op_sel:[1,0,0] op_sel_hi:[1,1,1]
	v_cndmask_b32_e64 v30, 0, v24, s[0:1]
	v_pk_fma_f32 v[2:3], v[44:45], v[22:23], v[84:85] op_sel:[0,0,0] op_sel_hi:[0,1,1] neg_lo:[1,0,0] neg_hi:[1,0,0]
	v_pk_fma_f32 v[4:5], v[44:45], v[22:23], v[86:87] op_sel:[1,0,0] op_sel_hi:[1,1,1] neg_lo:[1,0,0] neg_hi:[1,0,0]
	v_pk_fma_f32 v[6:7], v[46:47], v[22:23], v[88:89] op_sel:[0,0,0] op_sel_hi:[0,1,1] neg_lo:[1,0,0] neg_hi:[1,0,0]
	v_pk_fma_f32 v[8:9], v[46:47], v[22:23], v[90:91] op_sel:[1,0,0] op_sel_hi:[1,1,1] neg_lo:[1,0,0] neg_hi:[1,0,0]
	s_waitcnt lgkmcnt(0)
	v_pk_mul_f32 v[22:23], v[2:3], v[60:61] op_sel:[0,0] op_sel_hi:[1,0]
	v_pk_mul_f32 v[24:25], v[2:3], v[52:53] op_sel:[0,0] op_sel_hi:[1,0]
	ds_read_b128 v[36:39], v20 offset:1536
	v_pk_fma_f32 v[22:23], v[4:5], v[60:61], v[22:23] op_sel:[0,1,0] op_sel_hi:[1,1,1]
	v_pk_fma_f32 v[24:25], v[4:5], v[52:53], v[24:25] op_sel:[0,1,0] op_sel_hi:[1,1,1]
	ds_read_b128 v[40:43], v20 offset:9728
	v_pk_fma_f32 v[22:23], v[6:7], v[62:63], v[22:23] op_sel:[0,0,0] op_sel_hi:[1,0,1]
	v_pk_fma_f32 v[24:25], v[6:7], v[54:55], v[24:25] op_sel:[0,0,0] op_sel_hi:[1,0,1]
	ds_read_b64 v[56:57], v21 offset:42496
	v_pk_fma_f32 v[22:23], v[8:9], v[62:63], v[22:23] op_sel:[0,1,0] op_sel_hi:[1,1,1]
	v_pk_fma_f32 v[24:25], v[8:9], v[54:55], v[24:25] op_sel:[0,1,0] op_sel_hi:[1,1,1]
	ds_read_b128 v[48:51], v20 offset:26112
	ds_read_b128 v[44:47], v20 offset:17920
	ds_read_b128 v[52:55], v20 offset:34304
	v_add_f32_dpp v28, v28, v28 row_ror:12 row_mask:0xf bank_mask:0x5
	v_add_f32_dpp v29, v29, v29 row_ror:4 row_mask:0xf bank_mask:0xa
	v_add_f32_dpp v22, v22, v22 quad_perm:[1,0,3,2] row_mask:0xf bank_mask:0xf
	v_add_f32_dpp v23, v23, v23 quad_perm:[1,0,3,2] row_mask:0xf bank_mask:0xf
	v_pk_mul_f32 v[84:85], v[2:3], v[64:65] op_sel:[0,0] op_sel_hi:[1,0]
	v_pk_mul_f32 v[86:87], v[4:5], v[64:65] op_sel:[0,1] op_sel_hi:[1,1]
	v_add_f32_dpp v58, v58, v58 row_ror:12 row_mask:0xf bank_mask:0x5
	v_add_f32_dpp v22, v22, v22 quad_perm:[2,3,0,1] row_mask:0xf bank_mask:0xf
	v_add_f32_dpp v23, v23, v23 quad_perm:[2,3,0,1] row_mask:0xf bank_mask:0xf
	v_pk_mul_f32 v[88:89], v[6:7], v[66:67] op_sel:[0,0] op_sel_hi:[1,0]
	v_pk_mul_f32 v[90:91], v[8:9], v[66:67] op_sel:[0,1] op_sel_hi:[1,1]
	v_add_f32_dpp v59, v59, v59 row_ror:4 row_mask:0xf bank_mask:0xa
	v_add_f32_dpp v22, v22, v22 row_half_mirror row_mask:0xf bank_mask:0xf
	v_add_f32_dpp v23, v23, v23 row_half_mirror row_mask:0xf bank_mask:0xf
	v_pk_fma_f32 v[84:85], v[72:73], v[80:81], v[84:85] op_sel:[0,0,0] op_sel_hi:[0,1,1]
	v_pk_fma_f32 v[86:87], v[72:73], v[80:81], v[86:87] op_sel:[1,0,0] op_sel_hi:[1,1,1]
	v_mov_b32_dpp v28, v29 quad_perm:[0,1,2,3] row_mask:0xf bank_mask:0xa
	v_add_f32_dpp v22, v22, v22 row_mirror row_mask:0xf bank_mask:0xf
	v_add_f32_dpp v23, v23, v23 row_mirror row_mask:0xf bank_mask:0xf
	v_pk_fma_f32 v[88:89], v[74:75], v[80:81], v[88:89] op_sel:[0,0,0] op_sel_hi:[0,1,1]
	v_pk_fma_f32 v[90:91], v[74:75], v[80:81], v[90:91] op_sel:[1,0,0] op_sel_hi:[1,1,1]
	v_mov_b32_dpp v58, v59 quad_perm:[0,1,2,3] row_mask:0xf bank_mask:0xa
	v_pk_fma_f32 v[2:3], v[68:69], v[22:23], v[84:85] op_sel:[0,0,0] op_sel_hi:[0,1,1] neg_lo:[1,0,0] neg_hi:[1,0,0]
	v_pk_fma_f32 v[4:5], v[68:69], v[22:23], v[86:87] op_sel:[1,0,0] op_sel_hi:[1,1,1] neg_lo:[1,0,0] neg_hi:[1,0,0]
	v_pk_fma_f32 v[6:7], v[70:71], v[22:23], v[88:89] op_sel:[0,0,0] op_sel_hi:[0,1,1] neg_lo:[1,0,0] neg_hi:[1,0,0]
	v_pk_fma_f32 v[8:9], v[70:71], v[22:23], v[90:91] op_sel:[1,0,0] op_sel_hi:[1,1,1] neg_lo:[1,0,0] neg_hi:[1,0,0]
	s_waitcnt lgkmcnt(0)
	v_pk_mul_f32 v[22:23], v[2:3], v[36:37] op_sel:[0,0] op_sel_hi:[1,0]
	v_pk_mul_f32 v[26:27], v[2:3], v[76:77] op_sel:[0,0] op_sel_hi:[1,0]
	ds_read_b128 v[60:63], v20 offset:1792
	v_pk_fma_f32 v[22:23], v[4:5], v[36:37], v[22:23] op_sel:[0,1,0] op_sel_hi:[1,1,1]
	v_pk_fma_f32 v[26:27], v[4:5], v[76:77], v[26:27] op_sel:[0,1,0] op_sel_hi:[1,1,1]
	ds_read_b128 v[64:67], v20 offset:9984
	v_pk_fma_f32 v[22:23], v[6:7], v[38:39], v[22:23] op_sel:[0,0,0] op_sel_hi:[1,0,1]
	v_pk_fma_f32 v[26:27], v[6:7], v[78:79], v[26:27] op_sel:[0,0,0] op_sel_hi:[1,0,1]
	ds_read_b64 v[80:81], v21 offset:42752
	v_pk_fma_f32 v[22:23], v[8:9], v[38:39], v[22:23] op_sel:[0,1,0] op_sel_hi:[1,1,1]
	v_pk_fma_f32 v[26:27], v[8:9], v[78:79], v[26:27] op_sel:[0,1,0] op_sel_hi:[1,1,1]
	ds_read_b128 v[72:75], v20 offset:26368
	ds_read_b128 v[68:71], v20 offset:18176
	ds_read_b128 v[76:79], v20 offset:34560
	v_add_f32_dpp v28, v28, v28 row_ror:8 row_mask:0xf bank_mask:0x3
	v_add_f32_dpp v58, v58, v58 row_ror:8 row_mask:0xf bank_mask:0xc
	v_add_f32_dpp v22, v22, v22 quad_perm:[1,0,3,2] row_mask:0xf bank_mask:0xf
	v_add_f32_dpp v23, v23, v23 quad_perm:[1,0,3,2] row_mask:0xf bank_mask:0xf
	v_pk_mul_f32 v[84:85], v[2:3], v[40:41] op_sel:[0,0] op_sel_hi:[1,0]
	v_pk_mul_f32 v[86:87], v[4:5], v[40:41] op_sel:[0,1] op_sel_hi:[1,1]
	v_mov_b32_dpp v28, v58 quad_perm:[0,1,2,3] row_mask:0xf bank_mask:0xc
	v_add_f32_dpp v22, v22, v22 quad_perm:[2,3,0,1] row_mask:0xf bank_mask:0xf
	v_add_f32_dpp v23, v23, v23 quad_perm:[2,3,0,1] row_mask:0xf bank_mask:0xf
	v_pk_mul_f32 v[88:89], v[6:7], v[42:43] op_sel:[0,0] op_sel_hi:[1,0]
	v_pk_mul_f32 v[90:91], v[8:9], v[42:43] op_sel:[0,1] op_sel_hi:[1,1]
	v_add_f32_dpp v28, v28, v28 quad_perm:[1,0,3,2] row_mask:0xf bank_mask:0xf
	v_add_f32_dpp v22, v22, v22 row_half_mirror row_mask:0xf bank_mask:0xf
	v_add_f32_dpp v23, v23, v23 row_half_mirror row_mask:0xf bank_mask:0xf
	v_pk_fma_f32 v[84:85], v[48:49], v[56:57], v[84:85] op_sel:[0,0,0] op_sel_hi:[0,1,1]
	v_pk_fma_f32 v[86:87], v[48:49], v[56:57], v[86:87] op_sel:[1,0,0] op_sel_hi:[1,1,1]
	v_add_f32_dpp v28, v28, v28 quad_perm:[2,3,0,1] row_mask:0xf bank_mask:0xf
	v_add_f32_dpp v22, v22, v22 row_mirror row_mask:0xf bank_mask:0xf
	v_add_f32_dpp v23, v23, v23 row_mirror row_mask:0xf bank_mask:0xf
	v_pk_fma_f32 v[88:89], v[50:51], v[56:57], v[88:89] op_sel:[0,0,0] op_sel_hi:[0,1,1]
	v_pk_fma_f32 v[90:91], v[50:51], v[56:57], v[90:91] op_sel:[1,0,0] op_sel_hi:[1,1,1]
	v_cndmask_b32_e64 v30, v30, v28, s[6:7]
	v_pk_fma_f32 v[2:3], v[44:45], v[22:23], v[84:85] op_sel:[0,0,0] op_sel_hi:[0,1,1] neg_lo:[1,0,0] neg_hi:[1,0,0]
	v_pk_fma_f32 v[4:5], v[44:45], v[22:23], v[86:87] op_sel:[1,0,0] op_sel_hi:[1,1,1] neg_lo:[1,0,0] neg_hi:[1,0,0]
	v_pk_fma_f32 v[6:7], v[46:47], v[22:23], v[88:89] op_sel:[0,0,0] op_sel_hi:[0,1,1] neg_lo:[1,0,0] neg_hi:[1,0,0]
	v_pk_fma_f32 v[8:9], v[46:47], v[22:23], v[90:91] op_sel:[1,0,0] op_sel_hi:[1,1,1] neg_lo:[1,0,0] neg_hi:[1,0,0]
	s_waitcnt lgkmcnt(0)
	v_pk_mul_f32 v[22:23], v[2:3], v[60:61] op_sel:[0,0] op_sel_hi:[1,0]
	v_pk_mul_f32 v[28:29], v[2:3], v[52:53] op_sel:[0,0] op_sel_hi:[1,0]
	ds_read_b128 v[36:39], v20 offset:2048
	v_pk_fma_f32 v[22:23], v[4:5], v[60:61], v[22:23] op_sel:[0,1,0] op_sel_hi:[1,1,1]
	v_pk_fma_f32 v[28:29], v[4:5], v[52:53], v[28:29] op_sel:[0,1,0] op_sel_hi:[1,1,1]
	ds_read_b128 v[40:43], v20 offset:10240
	v_pk_fma_f32 v[22:23], v[6:7], v[62:63], v[22:23] op_sel:[0,0,0] op_sel_hi:[1,0,1]
	v_pk_fma_f32 v[28:29], v[6:7], v[54:55], v[28:29] op_sel:[0,0,0] op_sel_hi:[1,0,1]
	ds_read_b64 v[56:57], v21 offset:43008
	v_pk_fma_f32 v[22:23], v[8:9], v[62:63], v[22:23] op_sel:[0,1,0] op_sel_hi:[1,1,1]
	v_pk_fma_f32 v[28:29], v[8:9], v[54:55], v[28:29] op_sel:[0,1,0] op_sel_hi:[1,1,1]
	ds_read_b128 v[48:51], v20 offset:26624
	ds_read_b128 v[44:47], v20 offset:18432
	ds_read_b128 v[52:55], v20 offset:34816
	v_add_f32_dpp v24, v24, v24 row_ror:12 row_mask:0xf bank_mask:0x5
	v_add_f32_dpp v25, v25, v25 row_ror:4 row_mask:0xf bank_mask:0xa
	v_add_f32_dpp v22, v22, v22 quad_perm:[1,0,3,2] row_mask:0xf bank_mask:0xf
	v_add_f32_dpp v23, v23, v23 quad_perm:[1,0,3,2] row_mask:0xf bank_mask:0xf
	v_pk_mul_f32 v[84:85], v[2:3], v[64:65] op_sel:[0,0] op_sel_hi:[1,0]
	v_pk_mul_f32 v[86:87], v[4:5], v[64:65] op_sel:[0,1] op_sel_hi:[1,1]
	v_add_f32_dpp v26, v26, v26 row_ror:12 row_mask:0xf bank_mask:0x5
	v_add_f32_dpp v22, v22, v22 quad_perm:[2,3,0,1] row_mask:0xf bank_mask:0xf
	v_add_f32_dpp v23, v23, v23 quad_perm:[2,3,0,1] row_mask:0xf bank_mask:0xf
	v_pk_mul_f32 v[88:89], v[6:7], v[66:67] op_sel:[0,0] op_sel_hi:[1,0]
	v_pk_mul_f32 v[90:91], v[8:9], v[66:67] op_sel:[0,1] op_sel_hi:[1,1]
	v_add_f32_dpp v27, v27, v27 row_ror:4 row_mask:0xf bank_mask:0xa
	v_add_f32_dpp v22, v22, v22 row_half_mirror row_mask:0xf bank_mask:0xf
	v_add_f32_dpp v23, v23, v23 row_half_mirror row_mask:0xf bank_mask:0xf
	v_pk_fma_f32 v[84:85], v[72:73], v[80:81], v[84:85] op_sel:[0,0,0] op_sel_hi:[0,1,1]
	v_pk_fma_f32 v[86:87], v[72:73], v[80:81], v[86:87] op_sel:[1,0,0] op_sel_hi:[1,1,1]
	v_mov_b32_dpp v24, v25 quad_perm:[0,1,2,3] row_mask:0xf bank_mask:0xa
	v_add_f32_dpp v22, v22, v22 row_mirror row_mask:0xf bank_mask:0xf
	v_add_f32_dpp v23, v23, v23 row_mirror row_mask:0xf bank_mask:0xf
	v_pk_fma_f32 v[88:89], v[74:75], v[80:81], v[88:89] op_sel:[0,0,0] op_sel_hi:[0,1,1]
	v_pk_fma_f32 v[90:91], v[74:75], v[80:81], v[90:91] op_sel:[1,0,0] op_sel_hi:[1,1,1]
	v_mov_b32_dpp v26, v27 quad_perm:[0,1,2,3] row_mask:0xf bank_mask:0xa
	v_pk_fma_f32 v[2:3], v[68:69], v[22:23], v[84:85] op_sel:[0,0,0] op_sel_hi:[0,1,1] neg_lo:[1,0,0] neg_hi:[1,0,0]
	v_pk_fma_f32 v[4:5], v[68:69], v[22:23], v[86:87] op_sel:[1,0,0] op_sel_hi:[1,1,1] neg_lo:[1,0,0] neg_hi:[1,0,0]
	v_pk_fma_f32 v[6:7], v[70:71], v[22:23], v[88:89] op_sel:[0,0,0] op_sel_hi:[0,1,1] neg_lo:[1,0,0] neg_hi:[1,0,0]
	v_pk_fma_f32 v[8:9], v[70:71], v[22:23], v[90:91] op_sel:[1,0,0] op_sel_hi:[1,1,1] neg_lo:[1,0,0] neg_hi:[1,0,0]
	s_waitcnt lgkmcnt(0)
	v_pk_mul_f32 v[22:23], v[2:3], v[36:37] op_sel:[0,0] op_sel_hi:[1,0]
	v_pk_mul_f32 v[58:59], v[2:3], v[76:77] op_sel:[0,0] op_sel_hi:[1,0]
	ds_read_b128 v[60:63], v20 offset:2304
	v_pk_fma_f32 v[22:23], v[4:5], v[36:37], v[22:23] op_sel:[0,1,0] op_sel_hi:[1,1,1]
	v_pk_fma_f32 v[58:59], v[4:5], v[76:77], v[58:59] op_sel:[0,1,0] op_sel_hi:[1,1,1]
	ds_read_b128 v[64:67], v20 offset:10496
	v_pk_fma_f32 v[22:23], v[6:7], v[38:39], v[22:23] op_sel:[0,0,0] op_sel_hi:[1,0,1]
	v_pk_fma_f32 v[58:59], v[6:7], v[78:79], v[58:59] op_sel:[0,0,0] op_sel_hi:[1,0,1]
	ds_read_b64 v[80:81], v21 offset:43264
	v_pk_fma_f32 v[22:23], v[8:9], v[38:39], v[22:23] op_sel:[0,1,0] op_sel_hi:[1,1,1]
	v_pk_fma_f32 v[58:59], v[8:9], v[78:79], v[58:59] op_sel:[0,1,0] op_sel_hi:[1,1,1]
	ds_read_b128 v[72:75], v20 offset:26880
	ds_read_b128 v[68:71], v20 offset:18688
	ds_read_b128 v[76:79], v20 offset:35072
	v_add_f32_dpp v24, v24, v24 row_ror:8 row_mask:0xf bank_mask:0x3
	v_add_f32_dpp v26, v26, v26 row_ror:8 row_mask:0xf bank_mask:0xc
	v_add_f32_dpp v22, v22, v22 quad_perm:[1,0,3,2] row_mask:0xf bank_mask:0xf
	v_add_f32_dpp v23, v23, v23 quad_perm:[1,0,3,2] row_mask:0xf bank_mask:0xf
	v_pk_mul_f32 v[84:85], v[2:3], v[40:41] op_sel:[0,0] op_sel_hi:[1,0]
	v_pk_mul_f32 v[86:87], v[4:5], v[40:41] op_sel:[0,1] op_sel_hi:[1,1]
	v_mov_b32_dpp v24, v26 quad_perm:[0,1,2,3] row_mask:0xf bank_mask:0xc
	v_add_f32_dpp v22, v22, v22 quad_perm:[2,3,0,1] row_mask:0xf bank_mask:0xf
	v_add_f32_dpp v23, v23, v23 quad_perm:[2,3,0,1] row_mask:0xf bank_mask:0xf
	v_pk_mul_f32 v[88:89], v[6:7], v[42:43] op_sel:[0,0] op_sel_hi:[1,0]
	v_pk_mul_f32 v[90:91], v[8:9], v[42:43] op_sel:[0,1] op_sel_hi:[1,1]
	v_add_f32_dpp v24, v24, v24 quad_perm:[1,0,3,2] row_mask:0xf bank_mask:0xf
	v_add_f32_dpp v22, v22, v22 row_half_mirror row_mask:0xf bank_mask:0xf
	v_add_f32_dpp v23, v23, v23 row_half_mirror row_mask:0xf bank_mask:0xf
	v_pk_fma_f32 v[84:85], v[48:49], v[56:57], v[84:85] op_sel:[0,0,0] op_sel_hi:[0,1,1]
	v_pk_fma_f32 v[86:87], v[48:49], v[56:57], v[86:87] op_sel:[1,0,0] op_sel_hi:[1,1,1]
	v_add_f32_dpp v24, v24, v24 quad_perm:[2,3,0,1] row_mask:0xf bank_mask:0xf
	v_add_f32_dpp v22, v22, v22 row_mirror row_mask:0xf bank_mask:0xf
	v_add_f32_dpp v23, v23, v23 row_mirror row_mask:0xf bank_mask:0xf
	v_pk_fma_f32 v[88:89], v[50:51], v[56:57], v[88:89] op_sel:[0,0,0] op_sel_hi:[0,1,1]
	v_pk_fma_f32 v[90:91], v[50:51], v[56:57], v[90:91] op_sel:[1,0,0] op_sel_hi:[1,1,1]
	v_cndmask_b32_e64 v30, v30, v24, s[8:9]
	v_pk_fma_f32 v[2:3], v[44:45], v[22:23], v[84:85] op_sel:[0,0,0] op_sel_hi:[0,1,1] neg_lo:[1,0,0] neg_hi:[1,0,0]
	v_pk_fma_f32 v[4:5], v[44:45], v[22:23], v[86:87] op_sel:[1,0,0] op_sel_hi:[1,1,1] neg_lo:[1,0,0] neg_hi:[1,0,0]
	v_pk_fma_f32 v[6:7], v[46:47], v[22:23], v[88:89] op_sel:[0,0,0] op_sel_hi:[0,1,1] neg_lo:[1,0,0] neg_hi:[1,0,0]
	v_pk_fma_f32 v[8:9], v[46:47], v[22:23], v[90:91] op_sel:[1,0,0] op_sel_hi:[1,1,1] neg_lo:[1,0,0] neg_hi:[1,0,0]
	s_waitcnt lgkmcnt(0)
	v_pk_mul_f32 v[22:23], v[2:3], v[60:61] op_sel:[0,0] op_sel_hi:[1,0]
	v_pk_mul_f32 v[24:25], v[2:3], v[52:53] op_sel:[0,0] op_sel_hi:[1,0]
	ds_read_b128 v[36:39], v20 offset:2560
	v_pk_fma_f32 v[22:23], v[4:5], v[60:61], v[22:23] op_sel:[0,1,0] op_sel_hi:[1,1,1]
	v_pk_fma_f32 v[24:25], v[4:5], v[52:53], v[24:25] op_sel:[0,1,0] op_sel_hi:[1,1,1]
	ds_read_b128 v[40:43], v20 offset:10752
	v_pk_fma_f32 v[22:23], v[6:7], v[62:63], v[22:23] op_sel:[0,0,0] op_sel_hi:[1,0,1]
	v_pk_fma_f32 v[24:25], v[6:7], v[54:55], v[24:25] op_sel:[0,0,0] op_sel_hi:[1,0,1]
	ds_read_b64 v[56:57], v21 offset:43520
	v_pk_fma_f32 v[22:23], v[8:9], v[62:63], v[22:23] op_sel:[0,1,0] op_sel_hi:[1,1,1]
	v_pk_fma_f32 v[24:25], v[8:9], v[54:55], v[24:25] op_sel:[0,1,0] op_sel_hi:[1,1,1]
	ds_read_b128 v[48:51], v20 offset:27136
	ds_read_b128 v[44:47], v20 offset:18944
	ds_read_b128 v[52:55], v20 offset:35328
	v_add_f32_dpp v28, v28, v28 row_ror:12 row_mask:0xf bank_mask:0x5
	v_add_f32_dpp v29, v29, v29 row_ror:4 row_mask:0xf bank_mask:0xa
	v_add_f32_dpp v22, v22, v22 quad_perm:[1,0,3,2] row_mask:0xf bank_mask:0xf
	v_add_f32_dpp v23, v23, v23 quad_perm:[1,0,3,2] row_mask:0xf bank_mask:0xf
	v_pk_mul_f32 v[84:85], v[2:3], v[64:65] op_sel:[0,0] op_sel_hi:[1,0]
	v_pk_mul_f32 v[86:87], v[4:5], v[64:65] op_sel:[0,1] op_sel_hi:[1,1]
	v_add_f32_dpp v58, v58, v58 row_ror:12 row_mask:0xf bank_mask:0x5
	v_add_f32_dpp v22, v22, v22 quad_perm:[2,3,0,1] row_mask:0xf bank_mask:0xf
	v_add_f32_dpp v23, v23, v23 quad_perm:[2,3,0,1] row_mask:0xf bank_mask:0xf
	v_pk_mul_f32 v[88:89], v[6:7], v[66:67] op_sel:[0,0] op_sel_hi:[1,0]
	v_pk_mul_f32 v[90:91], v[8:9], v[66:67] op_sel:[0,1] op_sel_hi:[1,1]
	v_add_f32_dpp v59, v59, v59 row_ror:4 row_mask:0xf bank_mask:0xa
	v_add_f32_dpp v22, v22, v22 row_half_mirror row_mask:0xf bank_mask:0xf
	v_add_f32_dpp v23, v23, v23 row_half_mirror row_mask:0xf bank_mask:0xf
	v_pk_fma_f32 v[84:85], v[72:73], v[80:81], v[84:85] op_sel:[0,0,0] op_sel_hi:[0,1,1]
	v_pk_fma_f32 v[86:87], v[72:73], v[80:81], v[86:87] op_sel:[1,0,0] op_sel_hi:[1,1,1]
	v_mov_b32_dpp v28, v29 quad_perm:[0,1,2,3] row_mask:0xf bank_mask:0xa
	v_add_f32_dpp v22, v22, v22 row_mirror row_mask:0xf bank_mask:0xf
	v_add_f32_dpp v23, v23, v23 row_mirror row_mask:0xf bank_mask:0xf
	v_pk_fma_f32 v[88:89], v[74:75], v[80:81], v[88:89] op_sel:[0,0,0] op_sel_hi:[0,1,1]
	v_pk_fma_f32 v[90:91], v[74:75], v[80:81], v[90:91] op_sel:[1,0,0] op_sel_hi:[1,1,1]
	v_mov_b32_dpp v58, v59 quad_perm:[0,1,2,3] row_mask:0xf bank_mask:0xa
	v_pk_fma_f32 v[2:3], v[68:69], v[22:23], v[84:85] op_sel:[0,0,0] op_sel_hi:[0,1,1] neg_lo:[1,0,0] neg_hi:[1,0,0]
	v_pk_fma_f32 v[4:5], v[68:69], v[22:23], v[86:87] op_sel:[1,0,0] op_sel_hi:[1,1,1] neg_lo:[1,0,0] neg_hi:[1,0,0]
	v_pk_fma_f32 v[6:7], v[70:71], v[22:23], v[88:89] op_sel:[0,0,0] op_sel_hi:[0,1,1] neg_lo:[1,0,0] neg_hi:[1,0,0]
	v_pk_fma_f32 v[8:9], v[70:71], v[22:23], v[90:91] op_sel:[1,0,0] op_sel_hi:[1,1,1] neg_lo:[1,0,0] neg_hi:[1,0,0]
	s_waitcnt lgkmcnt(0)
	v_pk_mul_f32 v[22:23], v[2:3], v[36:37] op_sel:[0,0] op_sel_hi:[1,0]
	v_pk_mul_f32 v[26:27], v[2:3], v[76:77] op_sel:[0,0] op_sel_hi:[1,0]
	ds_read_b128 v[60:63], v20 offset:2816
	v_pk_fma_f32 v[22:23], v[4:5], v[36:37], v[22:23] op_sel:[0,1,0] op_sel_hi:[1,1,1]
	v_pk_fma_f32 v[26:27], v[4:5], v[76:77], v[26:27] op_sel:[0,1,0] op_sel_hi:[1,1,1]
	ds_read_b128 v[64:67], v20 offset:11008
	v_pk_fma_f32 v[22:23], v[6:7], v[38:39], v[22:23] op_sel:[0,0,0] op_sel_hi:[1,0,1]
	v_pk_fma_f32 v[26:27], v[6:7], v[78:79], v[26:27] op_sel:[0,0,0] op_sel_hi:[1,0,1]
	ds_read_b64 v[80:81], v21 offset:43776
	v_pk_fma_f32 v[22:23], v[8:9], v[38:39], v[22:23] op_sel:[0,1,0] op_sel_hi:[1,1,1]
	v_pk_fma_f32 v[26:27], v[8:9], v[78:79], v[26:27] op_sel:[0,1,0] op_sel_hi:[1,1,1]
	ds_read_b128 v[72:75], v20 offset:27392
	ds_read_b128 v[68:71], v20 offset:19200
	ds_read_b128 v[76:79], v20 offset:35584
	v_add_f32_dpp v28, v28, v28 row_ror:8 row_mask:0xf bank_mask:0x3
	v_add_f32_dpp v58, v58, v58 row_ror:8 row_mask:0xf bank_mask:0xc
	v_add_f32_dpp v22, v22, v22 quad_perm:[1,0,3,2] row_mask:0xf bank_mask:0xf
	v_add_f32_dpp v23, v23, v23 quad_perm:[1,0,3,2] row_mask:0xf bank_mask:0xf
	v_pk_mul_f32 v[84:85], v[2:3], v[40:41] op_sel:[0,0] op_sel_hi:[1,0]
	v_pk_mul_f32 v[86:87], v[4:5], v[40:41] op_sel:[0,1] op_sel_hi:[1,1]
	v_mov_b32_dpp v28, v58 quad_perm:[0,1,2,3] row_mask:0xf bank_mask:0xc
	v_add_f32_dpp v22, v22, v22 quad_perm:[2,3,0,1] row_mask:0xf bank_mask:0xf
	v_add_f32_dpp v23, v23, v23 quad_perm:[2,3,0,1] row_mask:0xf bank_mask:0xf
	v_pk_mul_f32 v[88:89], v[6:7], v[42:43] op_sel:[0,0] op_sel_hi:[1,0]
	v_pk_mul_f32 v[90:91], v[8:9], v[42:43] op_sel:[0,1] op_sel_hi:[1,1]
	v_add_f32_dpp v28, v28, v28 quad_perm:[1,0,3,2] row_mask:0xf bank_mask:0xf
	v_add_f32_dpp v22, v22, v22 row_half_mirror row_mask:0xf bank_mask:0xf
	v_add_f32_dpp v23, v23, v23 row_half_mirror row_mask:0xf bank_mask:0xf
	v_pk_fma_f32 v[84:85], v[48:49], v[56:57], v[84:85] op_sel:[0,0,0] op_sel_hi:[0,1,1]
	v_pk_fma_f32 v[86:87], v[48:49], v[56:57], v[86:87] op_sel:[1,0,0] op_sel_hi:[1,1,1]
	v_add_f32_dpp v28, v28, v28 quad_perm:[2,3,0,1] row_mask:0xf bank_mask:0xf
	v_add_f32_dpp v22, v22, v22 row_mirror row_mask:0xf bank_mask:0xf
	v_add_f32_dpp v23, v23, v23 row_mirror row_mask:0xf bank_mask:0xf
	v_pk_fma_f32 v[88:89], v[50:51], v[56:57], v[88:89] op_sel:[0,0,0] op_sel_hi:[0,1,1]
	v_pk_fma_f32 v[90:91], v[50:51], v[56:57], v[90:91] op_sel:[1,0,0] op_sel_hi:[1,1,1]
	v_cndmask_b32_e64 v30, v30, v28, s[10:11]
	v_pk_fma_f32 v[2:3], v[44:45], v[22:23], v[84:85] op_sel:[0,0,0] op_sel_hi:[0,1,1] neg_lo:[1,0,0] neg_hi:[1,0,0]
	v_pk_fma_f32 v[4:5], v[44:45], v[22:23], v[86:87] op_sel:[1,0,0] op_sel_hi:[1,1,1] neg_lo:[1,0,0] neg_hi:[1,0,0]
	v_pk_fma_f32 v[6:7], v[46:47], v[22:23], v[88:89] op_sel:[0,0,0] op_sel_hi:[0,1,1] neg_lo:[1,0,0] neg_hi:[1,0,0]
	v_pk_fma_f32 v[8:9], v[46:47], v[22:23], v[90:91] op_sel:[1,0,0] op_sel_hi:[1,1,1] neg_lo:[1,0,0] neg_hi:[1,0,0]
	s_waitcnt lgkmcnt(0)
	v_pk_mul_f32 v[22:23], v[2:3], v[60:61] op_sel:[0,0] op_sel_hi:[1,0]
	v_pk_mul_f32 v[28:29], v[2:3], v[52:53] op_sel:[0,0] op_sel_hi:[1,0]
	ds_read_b128 v[36:39], v20 offset:3072
	v_pk_fma_f32 v[22:23], v[4:5], v[60:61], v[22:23] op_sel:[0,1,0] op_sel_hi:[1,1,1]
	v_pk_fma_f32 v[28:29], v[4:5], v[52:53], v[28:29] op_sel:[0,1,0] op_sel_hi:[1,1,1]
	ds_read_b128 v[40:43], v20 offset:11264
	v_pk_fma_f32 v[22:23], v[6:7], v[62:63], v[22:23] op_sel:[0,0,0] op_sel_hi:[1,0,1]
	v_pk_fma_f32 v[28:29], v[6:7], v[54:55], v[28:29] op_sel:[0,0,0] op_sel_hi:[1,0,1]
	ds_read_b64 v[56:57], v21 offset:44032
	v_pk_fma_f32 v[22:23], v[8:9], v[62:63], v[22:23] op_sel:[0,1,0] op_sel_hi:[1,1,1]
	v_pk_fma_f32 v[28:29], v[8:9], v[54:55], v[28:29] op_sel:[0,1,0] op_sel_hi:[1,1,1]
	ds_read_b128 v[48:51], v20 offset:27648
	ds_read_b128 v[44:47], v20 offset:19456
	ds_read_b128 v[52:55], v20 offset:35840
	v_add_f32_dpp v24, v24, v24 row_ror:12 row_mask:0xf bank_mask:0x5
	v_add_f32_dpp v25, v25, v25 row_ror:4 row_mask:0xf bank_mask:0xa
	v_add_f32_dpp v22, v22, v22 quad_perm:[1,0,3,2] row_mask:0xf bank_mask:0xf
	v_add_f32_dpp v23, v23, v23 quad_perm:[1,0,3,2] row_mask:0xf bank_mask:0xf
	v_pk_mul_f32 v[84:85], v[2:3], v[64:65] op_sel:[0,0] op_sel_hi:[1,0]
	v_pk_mul_f32 v[86:87], v[4:5], v[64:65] op_sel:[0,1] op_sel_hi:[1,1]
	v_add_f32_dpp v26, v26, v26 row_ror:12 row_mask:0xf bank_mask:0x5
	v_add_f32_dpp v22, v22, v22 quad_perm:[2,3,0,1] row_mask:0xf bank_mask:0xf
	v_add_f32_dpp v23, v23, v23 quad_perm:[2,3,0,1] row_mask:0xf bank_mask:0xf
	v_pk_mul_f32 v[88:89], v[6:7], v[66:67] op_sel:[0,0] op_sel_hi:[1,0]
	v_pk_mul_f32 v[90:91], v[8:9], v[66:67] op_sel:[0,1] op_sel_hi:[1,1]
	v_add_f32_dpp v27, v27, v27 row_ror:4 row_mask:0xf bank_mask:0xa
	v_add_f32_dpp v22, v22, v22 row_half_mirror row_mask:0xf bank_mask:0xf
	v_add_f32_dpp v23, v23, v23 row_half_mirror row_mask:0xf bank_mask:0xf
	v_pk_fma_f32 v[84:85], v[72:73], v[80:81], v[84:85] op_sel:[0,0,0] op_sel_hi:[0,1,1]
	v_pk_fma_f32 v[86:87], v[72:73], v[80:81], v[86:87] op_sel:[1,0,0] op_sel_hi:[1,1,1]
	v_mov_b32_dpp v24, v25 quad_perm:[0,1,2,3] row_mask:0xf bank_mask:0xa
	v_add_f32_dpp v22, v22, v22 row_mirror row_mask:0xf bank_mask:0xf
	v_add_f32_dpp v23, v23, v23 row_mirror row_mask:0xf bank_mask:0xf
	v_pk_fma_f32 v[88:89], v[74:75], v[80:81], v[88:89] op_sel:[0,0,0] op_sel_hi:[0,1,1]
	v_pk_fma_f32 v[90:91], v[74:75], v[80:81], v[90:91] op_sel:[1,0,0] op_sel_hi:[1,1,1]
	v_mov_b32_dpp v26, v27 quad_perm:[0,1,2,3] row_mask:0xf bank_mask:0xa
	v_pk_fma_f32 v[2:3], v[68:69], v[22:23], v[84:85] op_sel:[0,0,0] op_sel_hi:[0,1,1] neg_lo:[1,0,0] neg_hi:[1,0,0]
	v_pk_fma_f32 v[4:5], v[68:69], v[22:23], v[86:87] op_sel:[1,0,0] op_sel_hi:[1,1,1] neg_lo:[1,0,0] neg_hi:[1,0,0]
	v_pk_fma_f32 v[6:7], v[70:71], v[22:23], v[88:89] op_sel:[0,0,0] op_sel_hi:[0,1,1] neg_lo:[1,0,0] neg_hi:[1,0,0]
	v_pk_fma_f32 v[8:9], v[70:71], v[22:23], v[90:91] op_sel:[1,0,0] op_sel_hi:[1,1,1] neg_lo:[1,0,0] neg_hi:[1,0,0]
	s_waitcnt lgkmcnt(0)
	v_pk_mul_f32 v[22:23], v[2:3], v[36:37] op_sel:[0,0] op_sel_hi:[1,0]
	v_pk_mul_f32 v[58:59], v[2:3], v[76:77] op_sel:[0,0] op_sel_hi:[1,0]
	ds_read_b128 v[60:63], v20 offset:3328
	v_pk_fma_f32 v[22:23], v[4:5], v[36:37], v[22:23] op_sel:[0,1,0] op_sel_hi:[1,1,1]
	v_pk_fma_f32 v[58:59], v[4:5], v[76:77], v[58:59] op_sel:[0,1,0] op_sel_hi:[1,1,1]
	ds_read_b128 v[64:67], v20 offset:11520
	v_pk_fma_f32 v[22:23], v[6:7], v[38:39], v[22:23] op_sel:[0,0,0] op_sel_hi:[1,0,1]
	v_pk_fma_f32 v[58:59], v[6:7], v[78:79], v[58:59] op_sel:[0,0,0] op_sel_hi:[1,0,1]
	ds_read_b64 v[80:81], v21 offset:44288
	v_pk_fma_f32 v[22:23], v[8:9], v[38:39], v[22:23] op_sel:[0,1,0] op_sel_hi:[1,1,1]
	v_pk_fma_f32 v[58:59], v[8:9], v[78:79], v[58:59] op_sel:[0,1,0] op_sel_hi:[1,1,1]
	ds_read_b128 v[72:75], v20 offset:27904
	ds_read_b128 v[68:71], v20 offset:19712
	ds_read_b128 v[76:79], v20 offset:36096
	v_add_f32_dpp v24, v24, v24 row_ror:8 row_mask:0xf bank_mask:0x3
	v_add_f32_dpp v26, v26, v26 row_ror:8 row_mask:0xf bank_mask:0xc
	v_add_f32_dpp v22, v22, v22 quad_perm:[1,0,3,2] row_mask:0xf bank_mask:0xf
	v_add_f32_dpp v23, v23, v23 quad_perm:[1,0,3,2] row_mask:0xf bank_mask:0xf
	v_pk_mul_f32 v[84:85], v[2:3], v[40:41] op_sel:[0,0] op_sel_hi:[1,0]
	v_pk_mul_f32 v[86:87], v[4:5], v[40:41] op_sel:[0,1] op_sel_hi:[1,1]
	v_mov_b32_dpp v24, v26 quad_perm:[0,1,2,3] row_mask:0xf bank_mask:0xc
	v_add_f32_dpp v22, v22, v22 quad_perm:[2,3,0,1] row_mask:0xf bank_mask:0xf
	v_add_f32_dpp v23, v23, v23 quad_perm:[2,3,0,1] row_mask:0xf bank_mask:0xf
	v_pk_mul_f32 v[88:89], v[6:7], v[42:43] op_sel:[0,0] op_sel_hi:[1,0]
	v_pk_mul_f32 v[90:91], v[8:9], v[42:43] op_sel:[0,1] op_sel_hi:[1,1]
	v_add_f32_dpp v24, v24, v24 quad_perm:[1,0,3,2] row_mask:0xf bank_mask:0xf
	v_add_f32_dpp v22, v22, v22 row_half_mirror row_mask:0xf bank_mask:0xf
	v_add_f32_dpp v23, v23, v23 row_half_mirror row_mask:0xf bank_mask:0xf
	v_pk_fma_f32 v[84:85], v[48:49], v[56:57], v[84:85] op_sel:[0,0,0] op_sel_hi:[0,1,1]
	v_pk_fma_f32 v[86:87], v[48:49], v[56:57], v[86:87] op_sel:[1,0,0] op_sel_hi:[1,1,1]
	v_add_f32_dpp v24, v24, v24 quad_perm:[2,3,0,1] row_mask:0xf bank_mask:0xf
	v_add_f32_dpp v22, v22, v22 row_mirror row_mask:0xf bank_mask:0xf
	v_add_f32_dpp v23, v23, v23 row_mirror row_mask:0xf bank_mask:0xf
	v_pk_fma_f32 v[88:89], v[50:51], v[56:57], v[88:89] op_sel:[0,0,0] op_sel_hi:[0,1,1]
	v_pk_fma_f32 v[90:91], v[50:51], v[56:57], v[90:91] op_sel:[1,0,0] op_sel_hi:[1,1,1]
	v_cndmask_b32_e64 v31, 0, v24, s[0:1]
	v_pk_fma_f32 v[2:3], v[44:45], v[22:23], v[84:85] op_sel:[0,0,0] op_sel_hi:[0,1,1] neg_lo:[1,0,0] neg_hi:[1,0,0]
	v_pk_fma_f32 v[4:5], v[44:45], v[22:23], v[86:87] op_sel:[1,0,0] op_sel_hi:[1,1,1] neg_lo:[1,0,0] neg_hi:[1,0,0]
	v_pk_fma_f32 v[6:7], v[46:47], v[22:23], v[88:89] op_sel:[0,0,0] op_sel_hi:[0,1,1] neg_lo:[1,0,0] neg_hi:[1,0,0]
	v_pk_fma_f32 v[8:9], v[46:47], v[22:23], v[90:91] op_sel:[1,0,0] op_sel_hi:[1,1,1] neg_lo:[1,0,0] neg_hi:[1,0,0]
	s_waitcnt lgkmcnt(0)
	v_pk_mul_f32 v[22:23], v[2:3], v[60:61] op_sel:[0,0] op_sel_hi:[1,0]
	v_pk_mul_f32 v[24:25], v[2:3], v[52:53] op_sel:[0,0] op_sel_hi:[1,0]
	ds_read_b128 v[36:39], v20 offset:3584
	v_pk_fma_f32 v[22:23], v[4:5], v[60:61], v[22:23] op_sel:[0,1,0] op_sel_hi:[1,1,1]
	v_pk_fma_f32 v[24:25], v[4:5], v[52:53], v[24:25] op_sel:[0,1,0] op_sel_hi:[1,1,1]
	ds_read_b128 v[40:43], v20 offset:11776
	v_pk_fma_f32 v[22:23], v[6:7], v[62:63], v[22:23] op_sel:[0,0,0] op_sel_hi:[1,0,1]
	v_pk_fma_f32 v[24:25], v[6:7], v[54:55], v[24:25] op_sel:[0,0,0] op_sel_hi:[1,0,1]
	ds_read_b64 v[56:57], v21 offset:44544
	v_pk_fma_f32 v[22:23], v[8:9], v[62:63], v[22:23] op_sel:[0,1,0] op_sel_hi:[1,1,1]
	v_pk_fma_f32 v[24:25], v[8:9], v[54:55], v[24:25] op_sel:[0,1,0] op_sel_hi:[1,1,1]
	ds_read_b128 v[48:51], v20 offset:28160
	ds_read_b128 v[44:47], v20 offset:19968
	ds_read_b128 v[52:55], v20 offset:36352
	v_add_f32_dpp v28, v28, v28 row_ror:12 row_mask:0xf bank_mask:0x5
	v_add_f32_dpp v29, v29, v29 row_ror:4 row_mask:0xf bank_mask:0xa
	v_add_f32_dpp v22, v22, v22 quad_perm:[1,0,3,2] row_mask:0xf bank_mask:0xf
	v_add_f32_dpp v23, v23, v23 quad_perm:[1,0,3,2] row_mask:0xf bank_mask:0xf
	v_pk_mul_f32 v[84:85], v[2:3], v[64:65] op_sel:[0,0] op_sel_hi:[1,0]
	v_pk_mul_f32 v[86:87], v[4:5], v[64:65] op_sel:[0,1] op_sel_hi:[1,1]
	v_add_f32_dpp v58, v58, v58 row_ror:12 row_mask:0xf bank_mask:0x5
	v_add_f32_dpp v22, v22, v22 quad_perm:[2,3,0,1] row_mask:0xf bank_mask:0xf
	v_add_f32_dpp v23, v23, v23 quad_perm:[2,3,0,1] row_mask:0xf bank_mask:0xf
	v_pk_mul_f32 v[88:89], v[6:7], v[66:67] op_sel:[0,0] op_sel_hi:[1,0]
	v_pk_mul_f32 v[90:91], v[8:9], v[66:67] op_sel:[0,1] op_sel_hi:[1,1]
	v_add_f32_dpp v59, v59, v59 row_ror:4 row_mask:0xf bank_mask:0xa
	v_add_f32_dpp v22, v22, v22 row_half_mirror row_mask:0xf bank_mask:0xf
	v_add_f32_dpp v23, v23, v23 row_half_mirror row_mask:0xf bank_mask:0xf
	v_pk_fma_f32 v[84:85], v[72:73], v[80:81], v[84:85] op_sel:[0,0,0] op_sel_hi:[0,1,1]
	v_pk_fma_f32 v[86:87], v[72:73], v[80:81], v[86:87] op_sel:[1,0,0] op_sel_hi:[1,1,1]
	v_mov_b32_dpp v28, v29 quad_perm:[0,1,2,3] row_mask:0xf bank_mask:0xa
	v_add_f32_dpp v22, v22, v22 row_mirror row_mask:0xf bank_mask:0xf
	v_add_f32_dpp v23, v23, v23 row_mirror row_mask:0xf bank_mask:0xf
	v_pk_fma_f32 v[88:89], v[74:75], v[80:81], v[88:89] op_sel:[0,0,0] op_sel_hi:[0,1,1]
	v_pk_fma_f32 v[90:91], v[74:75], v[80:81], v[90:91] op_sel:[1,0,0] op_sel_hi:[1,1,1]
	v_mov_b32_dpp v58, v59 quad_perm:[0,1,2,3] row_mask:0xf bank_mask:0xa
	v_pk_fma_f32 v[2:3], v[68:69], v[22:23], v[84:85] op_sel:[0,0,0] op_sel_hi:[0,1,1] neg_lo:[1,0,0] neg_hi:[1,0,0]
	v_pk_fma_f32 v[4:5], v[68:69], v[22:23], v[86:87] op_sel:[1,0,0] op_sel_hi:[1,1,1] neg_lo:[1,0,0] neg_hi:[1,0,0]
	v_pk_fma_f32 v[6:7], v[70:71], v[22:23], v[88:89] op_sel:[0,0,0] op_sel_hi:[0,1,1] neg_lo:[1,0,0] neg_hi:[1,0,0]
	v_pk_fma_f32 v[8:9], v[70:71], v[22:23], v[90:91] op_sel:[1,0,0] op_sel_hi:[1,1,1] neg_lo:[1,0,0] neg_hi:[1,0,0]
	s_waitcnt lgkmcnt(0)
	v_pk_mul_f32 v[22:23], v[2:3], v[36:37] op_sel:[0,0] op_sel_hi:[1,0]
	v_pk_mul_f32 v[26:27], v[2:3], v[76:77] op_sel:[0,0] op_sel_hi:[1,0]
	ds_read_b128 v[60:63], v20 offset:3840
	v_pk_fma_f32 v[22:23], v[4:5], v[36:37], v[22:23] op_sel:[0,1,0] op_sel_hi:[1,1,1]
	v_pk_fma_f32 v[26:27], v[4:5], v[76:77], v[26:27] op_sel:[0,1,0] op_sel_hi:[1,1,1]
	ds_read_b128 v[64:67], v20 offset:12032
	v_pk_fma_f32 v[22:23], v[6:7], v[38:39], v[22:23] op_sel:[0,0,0] op_sel_hi:[1,0,1]
	v_pk_fma_f32 v[26:27], v[6:7], v[78:79], v[26:27] op_sel:[0,0,0] op_sel_hi:[1,0,1]
	ds_read_b64 v[80:81], v21 offset:44800
	v_pk_fma_f32 v[22:23], v[8:9], v[38:39], v[22:23] op_sel:[0,1,0] op_sel_hi:[1,1,1]
	v_pk_fma_f32 v[26:27], v[8:9], v[78:79], v[26:27] op_sel:[0,1,0] op_sel_hi:[1,1,1]
	ds_read_b128 v[72:75], v20 offset:28416
	ds_read_b128 v[68:71], v20 offset:20224
	ds_read_b128 v[76:79], v20 offset:36608
	v_add_f32_dpp v28, v28, v28 row_ror:8 row_mask:0xf bank_mask:0x3
	v_add_f32_dpp v58, v58, v58 row_ror:8 row_mask:0xf bank_mask:0xc
	v_add_f32_dpp v22, v22, v22 quad_perm:[1,0,3,2] row_mask:0xf bank_mask:0xf
	v_add_f32_dpp v23, v23, v23 quad_perm:[1,0,3,2] row_mask:0xf bank_mask:0xf
	v_pk_mul_f32 v[84:85], v[2:3], v[40:41] op_sel:[0,0] op_sel_hi:[1,0]
	v_pk_mul_f32 v[86:87], v[4:5], v[40:41] op_sel:[0,1] op_sel_hi:[1,1]
	v_mov_b32_dpp v28, v58 quad_perm:[0,1,2,3] row_mask:0xf bank_mask:0xc
	v_add_f32_dpp v22, v22, v22 quad_perm:[2,3,0,1] row_mask:0xf bank_mask:0xf
	v_add_f32_dpp v23, v23, v23 quad_perm:[2,3,0,1] row_mask:0xf bank_mask:0xf
	v_pk_mul_f32 v[88:89], v[6:7], v[42:43] op_sel:[0,0] op_sel_hi:[1,0]
	v_pk_mul_f32 v[90:91], v[8:9], v[42:43] op_sel:[0,1] op_sel_hi:[1,1]
	v_add_f32_dpp v28, v28, v28 quad_perm:[1,0,3,2] row_mask:0xf bank_mask:0xf
	v_add_f32_dpp v22, v22, v22 row_half_mirror row_mask:0xf bank_mask:0xf
	v_add_f32_dpp v23, v23, v23 row_half_mirror row_mask:0xf bank_mask:0xf
	v_pk_fma_f32 v[84:85], v[48:49], v[56:57], v[84:85] op_sel:[0,0,0] op_sel_hi:[0,1,1]
	v_pk_fma_f32 v[86:87], v[48:49], v[56:57], v[86:87] op_sel:[1,0,0] op_sel_hi:[1,1,1]
	v_add_f32_dpp v28, v28, v28 quad_perm:[2,3,0,1] row_mask:0xf bank_mask:0xf
	v_add_f32_dpp v22, v22, v22 row_mirror row_mask:0xf bank_mask:0xf
	v_add_f32_dpp v23, v23, v23 row_mirror row_mask:0xf bank_mask:0xf
	v_pk_fma_f32 v[88:89], v[50:51], v[56:57], v[88:89] op_sel:[0,0,0] op_sel_hi:[0,1,1]
	v_pk_fma_f32 v[90:91], v[50:51], v[56:57], v[90:91] op_sel:[1,0,0] op_sel_hi:[1,1,1]
	v_cndmask_b32_e64 v31, v31, v28, s[6:7]
	v_pk_fma_f32 v[2:3], v[44:45], v[22:23], v[84:85] op_sel:[0,0,0] op_sel_hi:[0,1,1] neg_lo:[1,0,0] neg_hi:[1,0,0]
	v_pk_fma_f32 v[4:5], v[44:45], v[22:23], v[86:87] op_sel:[1,0,0] op_sel_hi:[1,1,1] neg_lo:[1,0,0] neg_hi:[1,0,0]
	v_pk_fma_f32 v[6:7], v[46:47], v[22:23], v[88:89] op_sel:[0,0,0] op_sel_hi:[0,1,1] neg_lo:[1,0,0] neg_hi:[1,0,0]
	v_pk_fma_f32 v[8:9], v[46:47], v[22:23], v[90:91] op_sel:[1,0,0] op_sel_hi:[1,1,1] neg_lo:[1,0,0] neg_hi:[1,0,0]
	s_waitcnt lgkmcnt(0)
	v_pk_mul_f32 v[22:23], v[2:3], v[60:61] op_sel:[0,0] op_sel_hi:[1,0]
	v_pk_mul_f32 v[28:29], v[2:3], v[52:53] op_sel:[0,0] op_sel_hi:[1,0]
	ds_read_b128 v[36:39], v20 offset:4096
	v_pk_fma_f32 v[22:23], v[4:5], v[60:61], v[22:23] op_sel:[0,1,0] op_sel_hi:[1,1,1]
	v_pk_fma_f32 v[28:29], v[4:5], v[52:53], v[28:29] op_sel:[0,1,0] op_sel_hi:[1,1,1]
	ds_read_b128 v[40:43], v20 offset:12288
	v_pk_fma_f32 v[22:23], v[6:7], v[62:63], v[22:23] op_sel:[0,0,0] op_sel_hi:[1,0,1]
	v_pk_fma_f32 v[28:29], v[6:7], v[54:55], v[28:29] op_sel:[0,0,0] op_sel_hi:[1,0,1]
	ds_read_b64 v[56:57], v21 offset:45056
	v_pk_fma_f32 v[22:23], v[8:9], v[62:63], v[22:23] op_sel:[0,1,0] op_sel_hi:[1,1,1]
	v_pk_fma_f32 v[28:29], v[8:9], v[54:55], v[28:29] op_sel:[0,1,0] op_sel_hi:[1,1,1]
	ds_read_b128 v[48:51], v20 offset:28672
	ds_read_b128 v[44:47], v20 offset:20480
	ds_read_b128 v[52:55], v20 offset:36864
	v_add_f32_dpp v24, v24, v24 row_ror:12 row_mask:0xf bank_mask:0x5
	v_add_f32_dpp v25, v25, v25 row_ror:4 row_mask:0xf bank_mask:0xa
	v_add_f32_dpp v22, v22, v22 quad_perm:[1,0,3,2] row_mask:0xf bank_mask:0xf
	v_add_f32_dpp v23, v23, v23 quad_perm:[1,0,3,2] row_mask:0xf bank_mask:0xf
	v_pk_mul_f32 v[84:85], v[2:3], v[64:65] op_sel:[0,0] op_sel_hi:[1,0]
	v_pk_mul_f32 v[86:87], v[4:5], v[64:65] op_sel:[0,1] op_sel_hi:[1,1]
	v_add_f32_dpp v26, v26, v26 row_ror:12 row_mask:0xf bank_mask:0x5
	v_add_f32_dpp v22, v22, v22 quad_perm:[2,3,0,1] row_mask:0xf bank_mask:0xf
	v_add_f32_dpp v23, v23, v23 quad_perm:[2,3,0,1] row_mask:0xf bank_mask:0xf
	v_pk_mul_f32 v[88:89], v[6:7], v[66:67] op_sel:[0,0] op_sel_hi:[1,0]
	v_pk_mul_f32 v[90:91], v[8:9], v[66:67] op_sel:[0,1] op_sel_hi:[1,1]
	v_add_f32_dpp v27, v27, v27 row_ror:4 row_mask:0xf bank_mask:0xa
	v_add_f32_dpp v22, v22, v22 row_half_mirror row_mask:0xf bank_mask:0xf
	v_add_f32_dpp v23, v23, v23 row_half_mirror row_mask:0xf bank_mask:0xf
	v_pk_fma_f32 v[84:85], v[72:73], v[80:81], v[84:85] op_sel:[0,0,0] op_sel_hi:[0,1,1]
	v_pk_fma_f32 v[86:87], v[72:73], v[80:81], v[86:87] op_sel:[1,0,0] op_sel_hi:[1,1,1]
	v_mov_b32_dpp v24, v25 quad_perm:[0,1,2,3] row_mask:0xf bank_mask:0xa
	v_add_f32_dpp v22, v22, v22 row_mirror row_mask:0xf bank_mask:0xf
	v_add_f32_dpp v23, v23, v23 row_mirror row_mask:0xf bank_mask:0xf
	v_pk_fma_f32 v[88:89], v[74:75], v[80:81], v[88:89] op_sel:[0,0,0] op_sel_hi:[0,1,1]
	v_pk_fma_f32 v[90:91], v[74:75], v[80:81], v[90:91] op_sel:[1,0,0] op_sel_hi:[1,1,1]
	v_mov_b32_dpp v26, v27 quad_perm:[0,1,2,3] row_mask:0xf bank_mask:0xa
	v_pk_fma_f32 v[2:3], v[68:69], v[22:23], v[84:85] op_sel:[0,0,0] op_sel_hi:[0,1,1] neg_lo:[1,0,0] neg_hi:[1,0,0]
	v_pk_fma_f32 v[4:5], v[68:69], v[22:23], v[86:87] op_sel:[1,0,0] op_sel_hi:[1,1,1] neg_lo:[1,0,0] neg_hi:[1,0,0]
	v_pk_fma_f32 v[6:7], v[70:71], v[22:23], v[88:89] op_sel:[0,0,0] op_sel_hi:[0,1,1] neg_lo:[1,0,0] neg_hi:[1,0,0]
	v_pk_fma_f32 v[8:9], v[70:71], v[22:23], v[90:91] op_sel:[1,0,0] op_sel_hi:[1,1,1] neg_lo:[1,0,0] neg_hi:[1,0,0]
	s_waitcnt lgkmcnt(0)
	v_pk_mul_f32 v[22:23], v[2:3], v[36:37] op_sel:[0,0] op_sel_hi:[1,0]
	v_pk_mul_f32 v[58:59], v[2:3], v[76:77] op_sel:[0,0] op_sel_hi:[1,0]
	ds_read_b128 v[60:63], v20 offset:4352
	v_pk_fma_f32 v[22:23], v[4:5], v[36:37], v[22:23] op_sel:[0,1,0] op_sel_hi:[1,1,1]
	v_pk_fma_f32 v[58:59], v[4:5], v[76:77], v[58:59] op_sel:[0,1,0] op_sel_hi:[1,1,1]
	ds_read_b128 v[64:67], v20 offset:12544
	v_pk_fma_f32 v[22:23], v[6:7], v[38:39], v[22:23] op_sel:[0,0,0] op_sel_hi:[1,0,1]
	v_pk_fma_f32 v[58:59], v[6:7], v[78:79], v[58:59] op_sel:[0,0,0] op_sel_hi:[1,0,1]
	ds_read_b64 v[80:81], v21 offset:45312
	v_pk_fma_f32 v[22:23], v[8:9], v[38:39], v[22:23] op_sel:[0,1,0] op_sel_hi:[1,1,1]
	v_pk_fma_f32 v[58:59], v[8:9], v[78:79], v[58:59] op_sel:[0,1,0] op_sel_hi:[1,1,1]
	ds_read_b128 v[72:75], v20 offset:28928
	ds_read_b128 v[68:71], v20 offset:20736
	ds_read_b128 v[76:79], v20 offset:37120
	v_add_f32_dpp v24, v24, v24 row_ror:8 row_mask:0xf bank_mask:0x3
	v_add_f32_dpp v26, v26, v26 row_ror:8 row_mask:0xf bank_mask:0xc
	v_add_f32_dpp v22, v22, v22 quad_perm:[1,0,3,2] row_mask:0xf bank_mask:0xf
	v_add_f32_dpp v23, v23, v23 quad_perm:[1,0,3,2] row_mask:0xf bank_mask:0xf
	v_pk_mul_f32 v[84:85], v[2:3], v[40:41] op_sel:[0,0] op_sel_hi:[1,0]
	v_pk_mul_f32 v[86:87], v[4:5], v[40:41] op_sel:[0,1] op_sel_hi:[1,1]
	v_mov_b32_dpp v24, v26 quad_perm:[0,1,2,3] row_mask:0xf bank_mask:0xc
	v_add_f32_dpp v22, v22, v22 quad_perm:[2,3,0,1] row_mask:0xf bank_mask:0xf
	v_add_f32_dpp v23, v23, v23 quad_perm:[2,3,0,1] row_mask:0xf bank_mask:0xf
	v_pk_mul_f32 v[88:89], v[6:7], v[42:43] op_sel:[0,0] op_sel_hi:[1,0]
	v_pk_mul_f32 v[90:91], v[8:9], v[42:43] op_sel:[0,1] op_sel_hi:[1,1]
	v_add_f32_dpp v24, v24, v24 quad_perm:[1,0,3,2] row_mask:0xf bank_mask:0xf
	v_add_f32_dpp v22, v22, v22 row_half_mirror row_mask:0xf bank_mask:0xf
	v_add_f32_dpp v23, v23, v23 row_half_mirror row_mask:0xf bank_mask:0xf
	v_pk_fma_f32 v[84:85], v[48:49], v[56:57], v[84:85] op_sel:[0,0,0] op_sel_hi:[0,1,1]
	v_pk_fma_f32 v[86:87], v[48:49], v[56:57], v[86:87] op_sel:[1,0,0] op_sel_hi:[1,1,1]
	v_add_f32_dpp v24, v24, v24 quad_perm:[2,3,0,1] row_mask:0xf bank_mask:0xf
	v_add_f32_dpp v22, v22, v22 row_mirror row_mask:0xf bank_mask:0xf
	v_add_f32_dpp v23, v23, v23 row_mirror row_mask:0xf bank_mask:0xf
	v_pk_fma_f32 v[88:89], v[50:51], v[56:57], v[88:89] op_sel:[0,0,0] op_sel_hi:[0,1,1]
	v_pk_fma_f32 v[90:91], v[50:51], v[56:57], v[90:91] op_sel:[1,0,0] op_sel_hi:[1,1,1]
	v_cndmask_b32_e64 v31, v31, v24, s[8:9]
	v_pk_fma_f32 v[2:3], v[44:45], v[22:23], v[84:85] op_sel:[0,0,0] op_sel_hi:[0,1,1] neg_lo:[1,0,0] neg_hi:[1,0,0]
	v_pk_fma_f32 v[4:5], v[44:45], v[22:23], v[86:87] op_sel:[1,0,0] op_sel_hi:[1,1,1] neg_lo:[1,0,0] neg_hi:[1,0,0]
	v_pk_fma_f32 v[6:7], v[46:47], v[22:23], v[88:89] op_sel:[0,0,0] op_sel_hi:[0,1,1] neg_lo:[1,0,0] neg_hi:[1,0,0]
	v_pk_fma_f32 v[8:9], v[46:47], v[22:23], v[90:91] op_sel:[1,0,0] op_sel_hi:[1,1,1] neg_lo:[1,0,0] neg_hi:[1,0,0]
	s_waitcnt lgkmcnt(0)
	v_pk_mul_f32 v[22:23], v[2:3], v[60:61] op_sel:[0,0] op_sel_hi:[1,0]
	v_pk_mul_f32 v[24:25], v[2:3], v[52:53] op_sel:[0,0] op_sel_hi:[1,0]
	ds_read_b128 v[36:39], v20 offset:4608
	v_pk_fma_f32 v[22:23], v[4:5], v[60:61], v[22:23] op_sel:[0,1,0] op_sel_hi:[1,1,1]
	v_pk_fma_f32 v[24:25], v[4:5], v[52:53], v[24:25] op_sel:[0,1,0] op_sel_hi:[1,1,1]
	ds_read_b128 v[40:43], v20 offset:12800
	v_pk_fma_f32 v[22:23], v[6:7], v[62:63], v[22:23] op_sel:[0,0,0] op_sel_hi:[1,0,1]
	v_pk_fma_f32 v[24:25], v[6:7], v[54:55], v[24:25] op_sel:[0,0,0] op_sel_hi:[1,0,1]
	ds_read_b64 v[56:57], v21 offset:45568
	v_pk_fma_f32 v[22:23], v[8:9], v[62:63], v[22:23] op_sel:[0,1,0] op_sel_hi:[1,1,1]
	v_pk_fma_f32 v[24:25], v[8:9], v[54:55], v[24:25] op_sel:[0,1,0] op_sel_hi:[1,1,1]
	ds_read_b128 v[48:51], v20 offset:29184
	ds_read_b128 v[44:47], v20 offset:20992
	ds_read_b128 v[52:55], v20 offset:37376
	v_add_f32_dpp v28, v28, v28 row_ror:12 row_mask:0xf bank_mask:0x5
	v_add_f32_dpp v29, v29, v29 row_ror:4 row_mask:0xf bank_mask:0xa
	v_add_f32_dpp v22, v22, v22 quad_perm:[1,0,3,2] row_mask:0xf bank_mask:0xf
	v_add_f32_dpp v23, v23, v23 quad_perm:[1,0,3,2] row_mask:0xf bank_mask:0xf
	v_pk_mul_f32 v[84:85], v[2:3], v[64:65] op_sel:[0,0] op_sel_hi:[1,0]
	v_pk_mul_f32 v[86:87], v[4:5], v[64:65] op_sel:[0,1] op_sel_hi:[1,1]
	v_add_f32_dpp v58, v58, v58 row_ror:12 row_mask:0xf bank_mask:0x5
	v_add_f32_dpp v22, v22, v22 quad_perm:[2,3,0,1] row_mask:0xf bank_mask:0xf
	v_add_f32_dpp v23, v23, v23 quad_perm:[2,3,0,1] row_mask:0xf bank_mask:0xf
	v_pk_mul_f32 v[88:89], v[6:7], v[66:67] op_sel:[0,0] op_sel_hi:[1,0]
	v_pk_mul_f32 v[90:91], v[8:9], v[66:67] op_sel:[0,1] op_sel_hi:[1,1]
	v_add_f32_dpp v59, v59, v59 row_ror:4 row_mask:0xf bank_mask:0xa
	v_add_f32_dpp v22, v22, v22 row_half_mirror row_mask:0xf bank_mask:0xf
	v_add_f32_dpp v23, v23, v23 row_half_mirror row_mask:0xf bank_mask:0xf
	v_pk_fma_f32 v[84:85], v[72:73], v[80:81], v[84:85] op_sel:[0,0,0] op_sel_hi:[0,1,1]
	v_pk_fma_f32 v[86:87], v[72:73], v[80:81], v[86:87] op_sel:[1,0,0] op_sel_hi:[1,1,1]
	v_mov_b32_dpp v28, v29 quad_perm:[0,1,2,3] row_mask:0xf bank_mask:0xa
	v_add_f32_dpp v22, v22, v22 row_mirror row_mask:0xf bank_mask:0xf
	v_add_f32_dpp v23, v23, v23 row_mirror row_mask:0xf bank_mask:0xf
	v_pk_fma_f32 v[88:89], v[74:75], v[80:81], v[88:89] op_sel:[0,0,0] op_sel_hi:[0,1,1]
	v_pk_fma_f32 v[90:91], v[74:75], v[80:81], v[90:91] op_sel:[1,0,0] op_sel_hi:[1,1,1]
	v_mov_b32_dpp v58, v59 quad_perm:[0,1,2,3] row_mask:0xf bank_mask:0xa
	v_pk_fma_f32 v[2:3], v[68:69], v[22:23], v[84:85] op_sel:[0,0,0] op_sel_hi:[0,1,1] neg_lo:[1,0,0] neg_hi:[1,0,0]
	v_pk_fma_f32 v[4:5], v[68:69], v[22:23], v[86:87] op_sel:[1,0,0] op_sel_hi:[1,1,1] neg_lo:[1,0,0] neg_hi:[1,0,0]
	v_pk_fma_f32 v[6:7], v[70:71], v[22:23], v[88:89] op_sel:[0,0,0] op_sel_hi:[0,1,1] neg_lo:[1,0,0] neg_hi:[1,0,0]
	v_pk_fma_f32 v[8:9], v[70:71], v[22:23], v[90:91] op_sel:[1,0,0] op_sel_hi:[1,1,1] neg_lo:[1,0,0] neg_hi:[1,0,0]
	s_waitcnt lgkmcnt(0)
	v_pk_mul_f32 v[22:23], v[2:3], v[36:37] op_sel:[0,0] op_sel_hi:[1,0]
	v_pk_mul_f32 v[26:27], v[2:3], v[76:77] op_sel:[0,0] op_sel_hi:[1,0]
	ds_read_b128 v[60:63], v20 offset:4864
	v_pk_fma_f32 v[22:23], v[4:5], v[36:37], v[22:23] op_sel:[0,1,0] op_sel_hi:[1,1,1]
	v_pk_fma_f32 v[26:27], v[4:5], v[76:77], v[26:27] op_sel:[0,1,0] op_sel_hi:[1,1,1]
	ds_read_b128 v[64:67], v20 offset:13056
	v_pk_fma_f32 v[22:23], v[6:7], v[38:39], v[22:23] op_sel:[0,0,0] op_sel_hi:[1,0,1]
	v_pk_fma_f32 v[26:27], v[6:7], v[78:79], v[26:27] op_sel:[0,0,0] op_sel_hi:[1,0,1]
	ds_read_b64 v[80:81], v21 offset:45824
	v_pk_fma_f32 v[22:23], v[8:9], v[38:39], v[22:23] op_sel:[0,1,0] op_sel_hi:[1,1,1]
	v_pk_fma_f32 v[26:27], v[8:9], v[78:79], v[26:27] op_sel:[0,1,0] op_sel_hi:[1,1,1]
	ds_read_b128 v[72:75], v20 offset:29440
	ds_read_b128 v[68:71], v20 offset:21248
	ds_read_b128 v[76:79], v20 offset:37632
	v_add_f32_dpp v28, v28, v28 row_ror:8 row_mask:0xf bank_mask:0x3
	v_add_f32_dpp v58, v58, v58 row_ror:8 row_mask:0xf bank_mask:0xc
	v_add_f32_dpp v22, v22, v22 quad_perm:[1,0,3,2] row_mask:0xf bank_mask:0xf
	v_add_f32_dpp v23, v23, v23 quad_perm:[1,0,3,2] row_mask:0xf bank_mask:0xf
	v_pk_mul_f32 v[84:85], v[2:3], v[40:41] op_sel:[0,0] op_sel_hi:[1,0]
	v_pk_mul_f32 v[86:87], v[4:5], v[40:41] op_sel:[0,1] op_sel_hi:[1,1]
	v_mov_b32_dpp v28, v58 quad_perm:[0,1,2,3] row_mask:0xf bank_mask:0xc
	v_add_f32_dpp v22, v22, v22 quad_perm:[2,3,0,1] row_mask:0xf bank_mask:0xf
	v_add_f32_dpp v23, v23, v23 quad_perm:[2,3,0,1] row_mask:0xf bank_mask:0xf
	v_pk_mul_f32 v[88:89], v[6:7], v[42:43] op_sel:[0,0] op_sel_hi:[1,0]
	v_pk_mul_f32 v[90:91], v[8:9], v[42:43] op_sel:[0,1] op_sel_hi:[1,1]
	v_add_f32_dpp v28, v28, v28 quad_perm:[1,0,3,2] row_mask:0xf bank_mask:0xf
	v_add_f32_dpp v22, v22, v22 row_half_mirror row_mask:0xf bank_mask:0xf
	v_add_f32_dpp v23, v23, v23 row_half_mirror row_mask:0xf bank_mask:0xf
	v_pk_fma_f32 v[84:85], v[48:49], v[56:57], v[84:85] op_sel:[0,0,0] op_sel_hi:[0,1,1]
	v_pk_fma_f32 v[86:87], v[48:49], v[56:57], v[86:87] op_sel:[1,0,0] op_sel_hi:[1,1,1]
	v_add_f32_dpp v28, v28, v28 quad_perm:[2,3,0,1] row_mask:0xf bank_mask:0xf
	v_add_f32_dpp v22, v22, v22 row_mirror row_mask:0xf bank_mask:0xf
	v_add_f32_dpp v23, v23, v23 row_mirror row_mask:0xf bank_mask:0xf
	v_pk_fma_f32 v[88:89], v[50:51], v[56:57], v[88:89] op_sel:[0,0,0] op_sel_hi:[0,1,1]
	v_pk_fma_f32 v[90:91], v[50:51], v[56:57], v[90:91] op_sel:[1,0,0] op_sel_hi:[1,1,1]
	v_cndmask_b32_e64 v31, v31, v28, s[10:11]
	v_pk_fma_f32 v[2:3], v[44:45], v[22:23], v[84:85] op_sel:[0,0,0] op_sel_hi:[0,1,1] neg_lo:[1,0,0] neg_hi:[1,0,0]
	v_pk_fma_f32 v[4:5], v[44:45], v[22:23], v[86:87] op_sel:[1,0,0] op_sel_hi:[1,1,1] neg_lo:[1,0,0] neg_hi:[1,0,0]
	v_pk_fma_f32 v[6:7], v[46:47], v[22:23], v[88:89] op_sel:[0,0,0] op_sel_hi:[0,1,1] neg_lo:[1,0,0] neg_hi:[1,0,0]
	v_pk_fma_f32 v[8:9], v[46:47], v[22:23], v[90:91] op_sel:[1,0,0] op_sel_hi:[1,1,1] neg_lo:[1,0,0] neg_hi:[1,0,0]
	s_waitcnt lgkmcnt(0)
	v_pk_mul_f32 v[22:23], v[2:3], v[60:61] op_sel:[0,0] op_sel_hi:[1,0]
	v_pk_mul_f32 v[28:29], v[2:3], v[52:53] op_sel:[0,0] op_sel_hi:[1,0]
	ds_read_b128 v[36:39], v20 offset:5120
	v_pk_fma_f32 v[22:23], v[4:5], v[60:61], v[22:23] op_sel:[0,1,0] op_sel_hi:[1,1,1]
	v_pk_fma_f32 v[28:29], v[4:5], v[52:53], v[28:29] op_sel:[0,1,0] op_sel_hi:[1,1,1]
	ds_read_b128 v[40:43], v20 offset:13312
	v_pk_fma_f32 v[22:23], v[6:7], v[62:63], v[22:23] op_sel:[0,0,0] op_sel_hi:[1,0,1]
	v_pk_fma_f32 v[28:29], v[6:7], v[54:55], v[28:29] op_sel:[0,0,0] op_sel_hi:[1,0,1]
	ds_read_b64 v[56:57], v21 offset:46080
	v_pk_fma_f32 v[22:23], v[8:9], v[62:63], v[22:23] op_sel:[0,1,0] op_sel_hi:[1,1,1]
	v_pk_fma_f32 v[28:29], v[8:9], v[54:55], v[28:29] op_sel:[0,1,0] op_sel_hi:[1,1,1]
	ds_read_b128 v[48:51], v20 offset:29696
	ds_read_b128 v[44:47], v20 offset:21504
	ds_read_b128 v[52:55], v20 offset:37888
	v_add_f32_dpp v24, v24, v24 row_ror:12 row_mask:0xf bank_mask:0x5
	v_add_f32_dpp v25, v25, v25 row_ror:4 row_mask:0xf bank_mask:0xa
	v_add_f32_dpp v22, v22, v22 quad_perm:[1,0,3,2] row_mask:0xf bank_mask:0xf
	v_add_f32_dpp v23, v23, v23 quad_perm:[1,0,3,2] row_mask:0xf bank_mask:0xf
	v_pk_mul_f32 v[84:85], v[2:3], v[64:65] op_sel:[0,0] op_sel_hi:[1,0]
	v_pk_mul_f32 v[86:87], v[4:5], v[64:65] op_sel:[0,1] op_sel_hi:[1,1]
	v_add_f32_dpp v26, v26, v26 row_ror:12 row_mask:0xf bank_mask:0x5
	v_add_f32_dpp v22, v22, v22 quad_perm:[2,3,0,1] row_mask:0xf bank_mask:0xf
	v_add_f32_dpp v23, v23, v23 quad_perm:[2,3,0,1] row_mask:0xf bank_mask:0xf
	v_pk_mul_f32 v[88:89], v[6:7], v[66:67] op_sel:[0,0] op_sel_hi:[1,0]
	v_pk_mul_f32 v[90:91], v[8:9], v[66:67] op_sel:[0,1] op_sel_hi:[1,1]
	v_add_f32_dpp v27, v27, v27 row_ror:4 row_mask:0xf bank_mask:0xa
	v_add_f32_dpp v22, v22, v22 row_half_mirror row_mask:0xf bank_mask:0xf
	v_add_f32_dpp v23, v23, v23 row_half_mirror row_mask:0xf bank_mask:0xf
	v_pk_fma_f32 v[84:85], v[72:73], v[80:81], v[84:85] op_sel:[0,0,0] op_sel_hi:[0,1,1]
	v_pk_fma_f32 v[86:87], v[72:73], v[80:81], v[86:87] op_sel:[1,0,0] op_sel_hi:[1,1,1]
	v_mov_b32_dpp v24, v25 quad_perm:[0,1,2,3] row_mask:0xf bank_mask:0xa
	v_add_f32_dpp v22, v22, v22 row_mirror row_mask:0xf bank_mask:0xf
	v_add_f32_dpp v23, v23, v23 row_mirror row_mask:0xf bank_mask:0xf
	v_pk_fma_f32 v[88:89], v[74:75], v[80:81], v[88:89] op_sel:[0,0,0] op_sel_hi:[0,1,1]
	v_pk_fma_f32 v[90:91], v[74:75], v[80:81], v[90:91] op_sel:[1,0,0] op_sel_hi:[1,1,1]
	v_mov_b32_dpp v26, v27 quad_perm:[0,1,2,3] row_mask:0xf bank_mask:0xa
	v_pk_fma_f32 v[2:3], v[68:69], v[22:23], v[84:85] op_sel:[0,0,0] op_sel_hi:[0,1,1] neg_lo:[1,0,0] neg_hi:[1,0,0]
	v_pk_fma_f32 v[4:5], v[68:69], v[22:23], v[86:87] op_sel:[1,0,0] op_sel_hi:[1,1,1] neg_lo:[1,0,0] neg_hi:[1,0,0]
	v_pk_fma_f32 v[6:7], v[70:71], v[22:23], v[88:89] op_sel:[0,0,0] op_sel_hi:[0,1,1] neg_lo:[1,0,0] neg_hi:[1,0,0]
	v_pk_fma_f32 v[8:9], v[70:71], v[22:23], v[90:91] op_sel:[1,0,0] op_sel_hi:[1,1,1] neg_lo:[1,0,0] neg_hi:[1,0,0]
	s_waitcnt lgkmcnt(0)
	v_pk_mul_f32 v[22:23], v[2:3], v[36:37] op_sel:[0,0] op_sel_hi:[1,0]
	v_pk_mul_f32 v[58:59], v[2:3], v[76:77] op_sel:[0,0] op_sel_hi:[1,0]
	ds_read_b128 v[60:63], v20 offset:5376
	v_pk_fma_f32 v[22:23], v[4:5], v[36:37], v[22:23] op_sel:[0,1,0] op_sel_hi:[1,1,1]
	v_pk_fma_f32 v[58:59], v[4:5], v[76:77], v[58:59] op_sel:[0,1,0] op_sel_hi:[1,1,1]
	ds_read_b128 v[64:67], v20 offset:13568
	v_pk_fma_f32 v[22:23], v[6:7], v[38:39], v[22:23] op_sel:[0,0,0] op_sel_hi:[1,0,1]
	v_pk_fma_f32 v[58:59], v[6:7], v[78:79], v[58:59] op_sel:[0,0,0] op_sel_hi:[1,0,1]
	ds_read_b64 v[80:81], v21 offset:46336
	v_pk_fma_f32 v[22:23], v[8:9], v[38:39], v[22:23] op_sel:[0,1,0] op_sel_hi:[1,1,1]
	v_pk_fma_f32 v[58:59], v[8:9], v[78:79], v[58:59] op_sel:[0,1,0] op_sel_hi:[1,1,1]
	ds_read_b128 v[72:75], v20 offset:29952
	ds_read_b128 v[68:71], v20 offset:21760
	ds_read_b128 v[76:79], v20 offset:38144
	v_add_f32_dpp v24, v24, v24 row_ror:8 row_mask:0xf bank_mask:0x3
	v_add_f32_dpp v26, v26, v26 row_ror:8 row_mask:0xf bank_mask:0xc
	v_add_f32_dpp v22, v22, v22 quad_perm:[1,0,3,2] row_mask:0xf bank_mask:0xf
	v_add_f32_dpp v23, v23, v23 quad_perm:[1,0,3,2] row_mask:0xf bank_mask:0xf
	v_pk_mul_f32 v[84:85], v[2:3], v[40:41] op_sel:[0,0] op_sel_hi:[1,0]
	v_pk_mul_f32 v[86:87], v[4:5], v[40:41] op_sel:[0,1] op_sel_hi:[1,1]
	v_mov_b32_dpp v24, v26 quad_perm:[0,1,2,3] row_mask:0xf bank_mask:0xc
	v_add_f32_dpp v22, v22, v22 quad_perm:[2,3,0,1] row_mask:0xf bank_mask:0xf
	v_add_f32_dpp v23, v23, v23 quad_perm:[2,3,0,1] row_mask:0xf bank_mask:0xf
	v_pk_mul_f32 v[88:89], v[6:7], v[42:43] op_sel:[0,0] op_sel_hi:[1,0]
	v_pk_mul_f32 v[90:91], v[8:9], v[42:43] op_sel:[0,1] op_sel_hi:[1,1]
	v_add_f32_dpp v24, v24, v24 quad_perm:[1,0,3,2] row_mask:0xf bank_mask:0xf
	v_add_f32_dpp v22, v22, v22 row_half_mirror row_mask:0xf bank_mask:0xf
	v_add_f32_dpp v23, v23, v23 row_half_mirror row_mask:0xf bank_mask:0xf
	v_pk_fma_f32 v[84:85], v[48:49], v[56:57], v[84:85] op_sel:[0,0,0] op_sel_hi:[0,1,1]
	v_pk_fma_f32 v[86:87], v[48:49], v[56:57], v[86:87] op_sel:[1,0,0] op_sel_hi:[1,1,1]
	v_add_f32_dpp v24, v24, v24 quad_perm:[2,3,0,1] row_mask:0xf bank_mask:0xf
	v_add_f32_dpp v22, v22, v22 row_mirror row_mask:0xf bank_mask:0xf
	v_add_f32_dpp v23, v23, v23 row_mirror row_mask:0xf bank_mask:0xf
	v_pk_fma_f32 v[88:89], v[50:51], v[56:57], v[88:89] op_sel:[0,0,0] op_sel_hi:[0,1,1]
	v_pk_fma_f32 v[90:91], v[50:51], v[56:57], v[90:91] op_sel:[1,0,0] op_sel_hi:[1,1,1]
	v_cndmask_b32_e64 v32, 0, v24, s[0:1]
	v_pk_fma_f32 v[2:3], v[44:45], v[22:23], v[84:85] op_sel:[0,0,0] op_sel_hi:[0,1,1] neg_lo:[1,0,0] neg_hi:[1,0,0]
	v_pk_fma_f32 v[4:5], v[44:45], v[22:23], v[86:87] op_sel:[1,0,0] op_sel_hi:[1,1,1] neg_lo:[1,0,0] neg_hi:[1,0,0]
	v_pk_fma_f32 v[6:7], v[46:47], v[22:23], v[88:89] op_sel:[0,0,0] op_sel_hi:[0,1,1] neg_lo:[1,0,0] neg_hi:[1,0,0]
	v_pk_fma_f32 v[8:9], v[46:47], v[22:23], v[90:91] op_sel:[1,0,0] op_sel_hi:[1,1,1] neg_lo:[1,0,0] neg_hi:[1,0,0]
	s_waitcnt lgkmcnt(0)
	v_pk_mul_f32 v[22:23], v[2:3], v[60:61] op_sel:[0,0] op_sel_hi:[1,0]
	v_pk_mul_f32 v[24:25], v[2:3], v[52:53] op_sel:[0,0] op_sel_hi:[1,0]
	ds_read_b128 v[36:39], v20 offset:5632
	v_pk_fma_f32 v[22:23], v[4:5], v[60:61], v[22:23] op_sel:[0,1,0] op_sel_hi:[1,1,1]
	v_pk_fma_f32 v[24:25], v[4:5], v[52:53], v[24:25] op_sel:[0,1,0] op_sel_hi:[1,1,1]
	ds_read_b128 v[40:43], v20 offset:13824
	v_pk_fma_f32 v[22:23], v[6:7], v[62:63], v[22:23] op_sel:[0,0,0] op_sel_hi:[1,0,1]
	v_pk_fma_f32 v[24:25], v[6:7], v[54:55], v[24:25] op_sel:[0,0,0] op_sel_hi:[1,0,1]
	ds_read_b64 v[56:57], v21 offset:46592
	v_pk_fma_f32 v[22:23], v[8:9], v[62:63], v[22:23] op_sel:[0,1,0] op_sel_hi:[1,1,1]
	v_pk_fma_f32 v[24:25], v[8:9], v[54:55], v[24:25] op_sel:[0,1,0] op_sel_hi:[1,1,1]
	ds_read_b128 v[48:51], v20 offset:30208
	ds_read_b128 v[44:47], v20 offset:22016
	ds_read_b128 v[52:55], v20 offset:38400
	v_add_f32_dpp v28, v28, v28 row_ror:12 row_mask:0xf bank_mask:0x5
	v_add_f32_dpp v29, v29, v29 row_ror:4 row_mask:0xf bank_mask:0xa
	v_add_f32_dpp v22, v22, v22 quad_perm:[1,0,3,2] row_mask:0xf bank_mask:0xf
	v_add_f32_dpp v23, v23, v23 quad_perm:[1,0,3,2] row_mask:0xf bank_mask:0xf
	v_pk_mul_f32 v[84:85], v[2:3], v[64:65] op_sel:[0,0] op_sel_hi:[1,0]
	v_pk_mul_f32 v[86:87], v[4:5], v[64:65] op_sel:[0,1] op_sel_hi:[1,1]
	v_add_f32_dpp v58, v58, v58 row_ror:12 row_mask:0xf bank_mask:0x5
	v_add_f32_dpp v22, v22, v22 quad_perm:[2,3,0,1] row_mask:0xf bank_mask:0xf
	v_add_f32_dpp v23, v23, v23 quad_perm:[2,3,0,1] row_mask:0xf bank_mask:0xf
	v_pk_mul_f32 v[88:89], v[6:7], v[66:67] op_sel:[0,0] op_sel_hi:[1,0]
	v_pk_mul_f32 v[90:91], v[8:9], v[66:67] op_sel:[0,1] op_sel_hi:[1,1]
	v_add_f32_dpp v59, v59, v59 row_ror:4 row_mask:0xf bank_mask:0xa
	v_add_f32_dpp v22, v22, v22 row_half_mirror row_mask:0xf bank_mask:0xf
	v_add_f32_dpp v23, v23, v23 row_half_mirror row_mask:0xf bank_mask:0xf
	v_pk_fma_f32 v[84:85], v[72:73], v[80:81], v[84:85] op_sel:[0,0,0] op_sel_hi:[0,1,1]
	v_pk_fma_f32 v[86:87], v[72:73], v[80:81], v[86:87] op_sel:[1,0,0] op_sel_hi:[1,1,1]
	v_mov_b32_dpp v28, v29 quad_perm:[0,1,2,3] row_mask:0xf bank_mask:0xa
	v_add_f32_dpp v22, v22, v22 row_mirror row_mask:0xf bank_mask:0xf
	v_add_f32_dpp v23, v23, v23 row_mirror row_mask:0xf bank_mask:0xf
	v_pk_fma_f32 v[88:89], v[74:75], v[80:81], v[88:89] op_sel:[0,0,0] op_sel_hi:[0,1,1]
	v_pk_fma_f32 v[90:91], v[74:75], v[80:81], v[90:91] op_sel:[1,0,0] op_sel_hi:[1,1,1]
	v_mov_b32_dpp v58, v59 quad_perm:[0,1,2,3] row_mask:0xf bank_mask:0xa
	v_pk_fma_f32 v[2:3], v[68:69], v[22:23], v[84:85] op_sel:[0,0,0] op_sel_hi:[0,1,1] neg_lo:[1,0,0] neg_hi:[1,0,0]
	v_pk_fma_f32 v[4:5], v[68:69], v[22:23], v[86:87] op_sel:[1,0,0] op_sel_hi:[1,1,1] neg_lo:[1,0,0] neg_hi:[1,0,0]
	v_pk_fma_f32 v[6:7], v[70:71], v[22:23], v[88:89] op_sel:[0,0,0] op_sel_hi:[0,1,1] neg_lo:[1,0,0] neg_hi:[1,0,0]
	v_pk_fma_f32 v[8:9], v[70:71], v[22:23], v[90:91] op_sel:[1,0,0] op_sel_hi:[1,1,1] neg_lo:[1,0,0] neg_hi:[1,0,0]
	s_waitcnt lgkmcnt(0)
	v_pk_mul_f32 v[22:23], v[2:3], v[36:37] op_sel:[0,0] op_sel_hi:[1,0]
	v_pk_mul_f32 v[26:27], v[2:3], v[76:77] op_sel:[0,0] op_sel_hi:[1,0]
	ds_read_b128 v[60:63], v20 offset:5888
	v_pk_fma_f32 v[22:23], v[4:5], v[36:37], v[22:23] op_sel:[0,1,0] op_sel_hi:[1,1,1]
	v_pk_fma_f32 v[26:27], v[4:5], v[76:77], v[26:27] op_sel:[0,1,0] op_sel_hi:[1,1,1]
	ds_read_b128 v[64:67], v20 offset:14080
	v_pk_fma_f32 v[22:23], v[6:7], v[38:39], v[22:23] op_sel:[0,0,0] op_sel_hi:[1,0,1]
	v_pk_fma_f32 v[26:27], v[6:7], v[78:79], v[26:27] op_sel:[0,0,0] op_sel_hi:[1,0,1]
	ds_read_b64 v[80:81], v21 offset:46848
	v_pk_fma_f32 v[22:23], v[8:9], v[38:39], v[22:23] op_sel:[0,1,0] op_sel_hi:[1,1,1]
	v_pk_fma_f32 v[26:27], v[8:9], v[78:79], v[26:27] op_sel:[0,1,0] op_sel_hi:[1,1,1]
	ds_read_b128 v[72:75], v20 offset:30464
	ds_read_b128 v[68:71], v20 offset:22272
	ds_read_b128 v[76:79], v20 offset:38656
	v_add_f32_dpp v28, v28, v28 row_ror:8 row_mask:0xf bank_mask:0x3
	v_add_f32_dpp v58, v58, v58 row_ror:8 row_mask:0xf bank_mask:0xc
	v_add_f32_dpp v22, v22, v22 quad_perm:[1,0,3,2] row_mask:0xf bank_mask:0xf
	v_add_f32_dpp v23, v23, v23 quad_perm:[1,0,3,2] row_mask:0xf bank_mask:0xf
	v_pk_mul_f32 v[84:85], v[2:3], v[40:41] op_sel:[0,0] op_sel_hi:[1,0]
	v_pk_mul_f32 v[86:87], v[4:5], v[40:41] op_sel:[0,1] op_sel_hi:[1,1]
	v_mov_b32_dpp v28, v58 quad_perm:[0,1,2,3] row_mask:0xf bank_mask:0xc
	v_add_f32_dpp v22, v22, v22 quad_perm:[2,3,0,1] row_mask:0xf bank_mask:0xf
	v_add_f32_dpp v23, v23, v23 quad_perm:[2,3,0,1] row_mask:0xf bank_mask:0xf
	v_pk_mul_f32 v[88:89], v[6:7], v[42:43] op_sel:[0,0] op_sel_hi:[1,0]
	v_pk_mul_f32 v[90:91], v[8:9], v[42:43] op_sel:[0,1] op_sel_hi:[1,1]
	v_add_f32_dpp v28, v28, v28 quad_perm:[1,0,3,2] row_mask:0xf bank_mask:0xf
	v_add_f32_dpp v22, v22, v22 row_half_mirror row_mask:0xf bank_mask:0xf
	v_add_f32_dpp v23, v23, v23 row_half_mirror row_mask:0xf bank_mask:0xf
	v_pk_fma_f32 v[84:85], v[48:49], v[56:57], v[84:85] op_sel:[0,0,0] op_sel_hi:[0,1,1]
	v_pk_fma_f32 v[86:87], v[48:49], v[56:57], v[86:87] op_sel:[1,0,0] op_sel_hi:[1,1,1]
	v_add_f32_dpp v28, v28, v28 quad_perm:[2,3,0,1] row_mask:0xf bank_mask:0xf
	v_add_f32_dpp v22, v22, v22 row_mirror row_mask:0xf bank_mask:0xf
	v_add_f32_dpp v23, v23, v23 row_mirror row_mask:0xf bank_mask:0xf
	v_pk_fma_f32 v[88:89], v[50:51], v[56:57], v[88:89] op_sel:[0,0,0] op_sel_hi:[0,1,1]
	v_pk_fma_f32 v[90:91], v[50:51], v[56:57], v[90:91] op_sel:[1,0,0] op_sel_hi:[1,1,1]
	v_cndmask_b32_e64 v32, v32, v28, s[6:7]
	v_pk_fma_f32 v[2:3], v[44:45], v[22:23], v[84:85] op_sel:[0,0,0] op_sel_hi:[0,1,1] neg_lo:[1,0,0] neg_hi:[1,0,0]
	v_pk_fma_f32 v[4:5], v[44:45], v[22:23], v[86:87] op_sel:[1,0,0] op_sel_hi:[1,1,1] neg_lo:[1,0,0] neg_hi:[1,0,0]
	v_pk_fma_f32 v[6:7], v[46:47], v[22:23], v[88:89] op_sel:[0,0,0] op_sel_hi:[0,1,1] neg_lo:[1,0,0] neg_hi:[1,0,0]
	v_pk_fma_f32 v[8:9], v[46:47], v[22:23], v[90:91] op_sel:[1,0,0] op_sel_hi:[1,1,1] neg_lo:[1,0,0] neg_hi:[1,0,0]
	s_waitcnt lgkmcnt(0)
	v_pk_mul_f32 v[22:23], v[2:3], v[60:61] op_sel:[0,0] op_sel_hi:[1,0]
	v_pk_mul_f32 v[28:29], v[2:3], v[52:53] op_sel:[0,0] op_sel_hi:[1,0]
	ds_read_b128 v[36:39], v20 offset:6144
	v_pk_fma_f32 v[22:23], v[4:5], v[60:61], v[22:23] op_sel:[0,1,0] op_sel_hi:[1,1,1]
	v_pk_fma_f32 v[28:29], v[4:5], v[52:53], v[28:29] op_sel:[0,1,0] op_sel_hi:[1,1,1]
	ds_read_b128 v[40:43], v20 offset:14336
	v_pk_fma_f32 v[22:23], v[6:7], v[62:63], v[22:23] op_sel:[0,0,0] op_sel_hi:[1,0,1]
	v_pk_fma_f32 v[28:29], v[6:7], v[54:55], v[28:29] op_sel:[0,0,0] op_sel_hi:[1,0,1]
	ds_read_b64 v[56:57], v21 offset:47104
	v_pk_fma_f32 v[22:23], v[8:9], v[62:63], v[22:23] op_sel:[0,1,0] op_sel_hi:[1,1,1]
	v_pk_fma_f32 v[28:29], v[8:9], v[54:55], v[28:29] op_sel:[0,1,0] op_sel_hi:[1,1,1]
	ds_read_b128 v[48:51], v20 offset:30720
	ds_read_b128 v[44:47], v20 offset:22528
	ds_read_b128 v[52:55], v20 offset:38912
	v_add_f32_dpp v24, v24, v24 row_ror:12 row_mask:0xf bank_mask:0x5
	v_add_f32_dpp v25, v25, v25 row_ror:4 row_mask:0xf bank_mask:0xa
	v_add_f32_dpp v22, v22, v22 quad_perm:[1,0,3,2] row_mask:0xf bank_mask:0xf
	v_add_f32_dpp v23, v23, v23 quad_perm:[1,0,3,2] row_mask:0xf bank_mask:0xf
	v_pk_mul_f32 v[84:85], v[2:3], v[64:65] op_sel:[0,0] op_sel_hi:[1,0]
	v_pk_mul_f32 v[86:87], v[4:5], v[64:65] op_sel:[0,1] op_sel_hi:[1,1]
	v_add_f32_dpp v26, v26, v26 row_ror:12 row_mask:0xf bank_mask:0x5
	v_add_f32_dpp v22, v22, v22 quad_perm:[2,3,0,1] row_mask:0xf bank_mask:0xf
	v_add_f32_dpp v23, v23, v23 quad_perm:[2,3,0,1] row_mask:0xf bank_mask:0xf
	v_pk_mul_f32 v[88:89], v[6:7], v[66:67] op_sel:[0,0] op_sel_hi:[1,0]
	v_pk_mul_f32 v[90:91], v[8:9], v[66:67] op_sel:[0,1] op_sel_hi:[1,1]
	v_add_f32_dpp v27, v27, v27 row_ror:4 row_mask:0xf bank_mask:0xa
	v_add_f32_dpp v22, v22, v22 row_half_mirror row_mask:0xf bank_mask:0xf
	v_add_f32_dpp v23, v23, v23 row_half_mirror row_mask:0xf bank_mask:0xf
	v_pk_fma_f32 v[84:85], v[72:73], v[80:81], v[84:85] op_sel:[0,0,0] op_sel_hi:[0,1,1]
	v_pk_fma_f32 v[86:87], v[72:73], v[80:81], v[86:87] op_sel:[1,0,0] op_sel_hi:[1,1,1]
	v_mov_b32_dpp v24, v25 quad_perm:[0,1,2,3] row_mask:0xf bank_mask:0xa
	v_add_f32_dpp v22, v22, v22 row_mirror row_mask:0xf bank_mask:0xf
	v_add_f32_dpp v23, v23, v23 row_mirror row_mask:0xf bank_mask:0xf
	v_pk_fma_f32 v[88:89], v[74:75], v[80:81], v[88:89] op_sel:[0,0,0] op_sel_hi:[0,1,1]
	v_pk_fma_f32 v[90:91], v[74:75], v[80:81], v[90:91] op_sel:[1,0,0] op_sel_hi:[1,1,1]
	v_mov_b32_dpp v26, v27 quad_perm:[0,1,2,3] row_mask:0xf bank_mask:0xa
	v_pk_fma_f32 v[2:3], v[68:69], v[22:23], v[84:85] op_sel:[0,0,0] op_sel_hi:[0,1,1] neg_lo:[1,0,0] neg_hi:[1,0,0]
	v_pk_fma_f32 v[4:5], v[68:69], v[22:23], v[86:87] op_sel:[1,0,0] op_sel_hi:[1,1,1] neg_lo:[1,0,0] neg_hi:[1,0,0]
	v_pk_fma_f32 v[6:7], v[70:71], v[22:23], v[88:89] op_sel:[0,0,0] op_sel_hi:[0,1,1] neg_lo:[1,0,0] neg_hi:[1,0,0]
	v_pk_fma_f32 v[8:9], v[70:71], v[22:23], v[90:91] op_sel:[1,0,0] op_sel_hi:[1,1,1] neg_lo:[1,0,0] neg_hi:[1,0,0]
	s_waitcnt lgkmcnt(0)
	v_pk_mul_f32 v[22:23], v[2:3], v[36:37] op_sel:[0,0] op_sel_hi:[1,0]
	v_pk_mul_f32 v[58:59], v[2:3], v[76:77] op_sel:[0,0] op_sel_hi:[1,0]
	ds_read_b128 v[60:63], v20 offset:6400
	v_pk_fma_f32 v[22:23], v[4:5], v[36:37], v[22:23] op_sel:[0,1,0] op_sel_hi:[1,1,1]
	v_pk_fma_f32 v[58:59], v[4:5], v[76:77], v[58:59] op_sel:[0,1,0] op_sel_hi:[1,1,1]
	ds_read_b128 v[64:67], v20 offset:14592
	v_pk_fma_f32 v[22:23], v[6:7], v[38:39], v[22:23] op_sel:[0,0,0] op_sel_hi:[1,0,1]
	v_pk_fma_f32 v[58:59], v[6:7], v[78:79], v[58:59] op_sel:[0,0,0] op_sel_hi:[1,0,1]
	ds_read_b64 v[80:81], v21 offset:47360
	v_pk_fma_f32 v[22:23], v[8:9], v[38:39], v[22:23] op_sel:[0,1,0] op_sel_hi:[1,1,1]
	v_pk_fma_f32 v[58:59], v[8:9], v[78:79], v[58:59] op_sel:[0,1,0] op_sel_hi:[1,1,1]
	ds_read_b128 v[72:75], v20 offset:30976
	ds_read_b128 v[68:71], v20 offset:22784
	ds_read_b128 v[76:79], v20 offset:39168
	v_add_f32_dpp v24, v24, v24 row_ror:8 row_mask:0xf bank_mask:0x3
	v_add_f32_dpp v26, v26, v26 row_ror:8 row_mask:0xf bank_mask:0xc
	v_add_f32_dpp v22, v22, v22 quad_perm:[1,0,3,2] row_mask:0xf bank_mask:0xf
	v_add_f32_dpp v23, v23, v23 quad_perm:[1,0,3,2] row_mask:0xf bank_mask:0xf
	v_pk_mul_f32 v[84:85], v[2:3], v[40:41] op_sel:[0,0] op_sel_hi:[1,0]
	v_pk_mul_f32 v[86:87], v[4:5], v[40:41] op_sel:[0,1] op_sel_hi:[1,1]
	v_mov_b32_dpp v24, v26 quad_perm:[0,1,2,3] row_mask:0xf bank_mask:0xc
	v_add_f32_dpp v22, v22, v22 quad_perm:[2,3,0,1] row_mask:0xf bank_mask:0xf
	v_add_f32_dpp v23, v23, v23 quad_perm:[2,3,0,1] row_mask:0xf bank_mask:0xf
	v_pk_mul_f32 v[88:89], v[6:7], v[42:43] op_sel:[0,0] op_sel_hi:[1,0]
	v_pk_mul_f32 v[90:91], v[8:9], v[42:43] op_sel:[0,1] op_sel_hi:[1,1]
	v_add_f32_dpp v24, v24, v24 quad_perm:[1,0,3,2] row_mask:0xf bank_mask:0xf
	v_add_f32_dpp v22, v22, v22 row_half_mirror row_mask:0xf bank_mask:0xf
	v_add_f32_dpp v23, v23, v23 row_half_mirror row_mask:0xf bank_mask:0xf
	v_pk_fma_f32 v[84:85], v[48:49], v[56:57], v[84:85] op_sel:[0,0,0] op_sel_hi:[0,1,1]
	v_pk_fma_f32 v[86:87], v[48:49], v[56:57], v[86:87] op_sel:[1,0,0] op_sel_hi:[1,1,1]
	v_add_f32_dpp v24, v24, v24 quad_perm:[2,3,0,1] row_mask:0xf bank_mask:0xf
	v_add_f32_dpp v22, v22, v22 row_mirror row_mask:0xf bank_mask:0xf
	v_add_f32_dpp v23, v23, v23 row_mirror row_mask:0xf bank_mask:0xf
	v_pk_fma_f32 v[88:89], v[50:51], v[56:57], v[88:89] op_sel:[0,0,0] op_sel_hi:[0,1,1]
	v_pk_fma_f32 v[90:91], v[50:51], v[56:57], v[90:91] op_sel:[1,0,0] op_sel_hi:[1,1,1]
	v_cndmask_b32_e64 v32, v32, v24, s[8:9]
	v_pk_fma_f32 v[2:3], v[44:45], v[22:23], v[84:85] op_sel:[0,0,0] op_sel_hi:[0,1,1] neg_lo:[1,0,0] neg_hi:[1,0,0]
	v_pk_fma_f32 v[4:5], v[44:45], v[22:23], v[86:87] op_sel:[1,0,0] op_sel_hi:[1,1,1] neg_lo:[1,0,0] neg_hi:[1,0,0]
	v_pk_fma_f32 v[6:7], v[46:47], v[22:23], v[88:89] op_sel:[0,0,0] op_sel_hi:[0,1,1] neg_lo:[1,0,0] neg_hi:[1,0,0]
	v_pk_fma_f32 v[8:9], v[46:47], v[22:23], v[90:91] op_sel:[1,0,0] op_sel_hi:[1,1,1] neg_lo:[1,0,0] neg_hi:[1,0,0]
	s_waitcnt lgkmcnt(0)
	v_pk_mul_f32 v[22:23], v[2:3], v[60:61] op_sel:[0,0] op_sel_hi:[1,0]
	v_pk_mul_f32 v[24:25], v[2:3], v[52:53] op_sel:[0,0] op_sel_hi:[1,0]
	ds_read_b128 v[36:39], v20 offset:6656
	v_pk_fma_f32 v[22:23], v[4:5], v[60:61], v[22:23] op_sel:[0,1,0] op_sel_hi:[1,1,1]
	v_pk_fma_f32 v[24:25], v[4:5], v[52:53], v[24:25] op_sel:[0,1,0] op_sel_hi:[1,1,1]
	ds_read_b128 v[40:43], v20 offset:14848
	v_pk_fma_f32 v[22:23], v[6:7], v[62:63], v[22:23] op_sel:[0,0,0] op_sel_hi:[1,0,1]
	v_pk_fma_f32 v[24:25], v[6:7], v[54:55], v[24:25] op_sel:[0,0,0] op_sel_hi:[1,0,1]
	ds_read_b64 v[56:57], v21 offset:47616
	v_pk_fma_f32 v[22:23], v[8:9], v[62:63], v[22:23] op_sel:[0,1,0] op_sel_hi:[1,1,1]
	v_pk_fma_f32 v[24:25], v[8:9], v[54:55], v[24:25] op_sel:[0,1,0] op_sel_hi:[1,1,1]
	ds_read_b128 v[48:51], v20 offset:31232
	ds_read_b128 v[44:47], v20 offset:23040
	ds_read_b128 v[52:55], v20 offset:39424
	v_add_f32_dpp v28, v28, v28 row_ror:12 row_mask:0xf bank_mask:0x5
	v_add_f32_dpp v29, v29, v29 row_ror:4 row_mask:0xf bank_mask:0xa
	v_add_f32_dpp v22, v22, v22 quad_perm:[1,0,3,2] row_mask:0xf bank_mask:0xf
	v_add_f32_dpp v23, v23, v23 quad_perm:[1,0,3,2] row_mask:0xf bank_mask:0xf
	v_pk_mul_f32 v[84:85], v[2:3], v[64:65] op_sel:[0,0] op_sel_hi:[1,0]
	v_pk_mul_f32 v[86:87], v[4:5], v[64:65] op_sel:[0,1] op_sel_hi:[1,1]
	v_add_f32_dpp v58, v58, v58 row_ror:12 row_mask:0xf bank_mask:0x5
	v_add_f32_dpp v22, v22, v22 quad_perm:[2,3,0,1] row_mask:0xf bank_mask:0xf
	v_add_f32_dpp v23, v23, v23 quad_perm:[2,3,0,1] row_mask:0xf bank_mask:0xf
	v_pk_mul_f32 v[88:89], v[6:7], v[66:67] op_sel:[0,0] op_sel_hi:[1,0]
	v_pk_mul_f32 v[90:91], v[8:9], v[66:67] op_sel:[0,1] op_sel_hi:[1,1]
	v_add_f32_dpp v59, v59, v59 row_ror:4 row_mask:0xf bank_mask:0xa
	v_add_f32_dpp v22, v22, v22 row_half_mirror row_mask:0xf bank_mask:0xf
	v_add_f32_dpp v23, v23, v23 row_half_mirror row_mask:0xf bank_mask:0xf
	v_pk_fma_f32 v[84:85], v[72:73], v[80:81], v[84:85] op_sel:[0,0,0] op_sel_hi:[0,1,1]
	v_pk_fma_f32 v[86:87], v[72:73], v[80:81], v[86:87] op_sel:[1,0,0] op_sel_hi:[1,1,1]
	v_mov_b32_dpp v28, v29 quad_perm:[0,1,2,3] row_mask:0xf bank_mask:0xa
	v_add_f32_dpp v22, v22, v22 row_mirror row_mask:0xf bank_mask:0xf
	v_add_f32_dpp v23, v23, v23 row_mirror row_mask:0xf bank_mask:0xf
	v_pk_fma_f32 v[88:89], v[74:75], v[80:81], v[88:89] op_sel:[0,0,0] op_sel_hi:[0,1,1]
	v_pk_fma_f32 v[90:91], v[74:75], v[80:81], v[90:91] op_sel:[1,0,0] op_sel_hi:[1,1,1]
	v_mov_b32_dpp v58, v59 quad_perm:[0,1,2,3] row_mask:0xf bank_mask:0xa
	v_pk_fma_f32 v[2:3], v[68:69], v[22:23], v[84:85] op_sel:[0,0,0] op_sel_hi:[0,1,1] neg_lo:[1,0,0] neg_hi:[1,0,0]
	v_pk_fma_f32 v[4:5], v[68:69], v[22:23], v[86:87] op_sel:[1,0,0] op_sel_hi:[1,1,1] neg_lo:[1,0,0] neg_hi:[1,0,0]
	v_pk_fma_f32 v[6:7], v[70:71], v[22:23], v[88:89] op_sel:[0,0,0] op_sel_hi:[0,1,1] neg_lo:[1,0,0] neg_hi:[1,0,0]
	v_pk_fma_f32 v[8:9], v[70:71], v[22:23], v[90:91] op_sel:[1,0,0] op_sel_hi:[1,1,1] neg_lo:[1,0,0] neg_hi:[1,0,0]
	s_waitcnt lgkmcnt(0)
	v_pk_mul_f32 v[22:23], v[2:3], v[36:37] op_sel:[0,0] op_sel_hi:[1,0]
	v_pk_mul_f32 v[26:27], v[2:3], v[76:77] op_sel:[0,0] op_sel_hi:[1,0]
	ds_read_b128 v[60:63], v20 offset:6912
	v_pk_fma_f32 v[22:23], v[4:5], v[36:37], v[22:23] op_sel:[0,1,0] op_sel_hi:[1,1,1]
	v_pk_fma_f32 v[26:27], v[4:5], v[76:77], v[26:27] op_sel:[0,1,0] op_sel_hi:[1,1,1]
	ds_read_b128 v[64:67], v20 offset:15104
	v_pk_fma_f32 v[22:23], v[6:7], v[38:39], v[22:23] op_sel:[0,0,0] op_sel_hi:[1,0,1]
	v_pk_fma_f32 v[26:27], v[6:7], v[78:79], v[26:27] op_sel:[0,0,0] op_sel_hi:[1,0,1]
	ds_read_b64 v[80:81], v21 offset:47872
	v_pk_fma_f32 v[22:23], v[8:9], v[38:39], v[22:23] op_sel:[0,1,0] op_sel_hi:[1,1,1]
	v_pk_fma_f32 v[26:27], v[8:9], v[78:79], v[26:27] op_sel:[0,1,0] op_sel_hi:[1,1,1]
	ds_read_b128 v[72:75], v20 offset:31488
	ds_read_b128 v[68:71], v20 offset:23296
	ds_read_b128 v[76:79], v20 offset:39680
	v_add_f32_dpp v28, v28, v28 row_ror:8 row_mask:0xf bank_mask:0x3
	v_add_f32_dpp v58, v58, v58 row_ror:8 row_mask:0xf bank_mask:0xc
	v_add_f32_dpp v22, v22, v22 quad_perm:[1,0,3,2] row_mask:0xf bank_mask:0xf
	v_add_f32_dpp v23, v23, v23 quad_perm:[1,0,3,2] row_mask:0xf bank_mask:0xf
	v_pk_mul_f32 v[84:85], v[2:3], v[40:41] op_sel:[0,0] op_sel_hi:[1,0]
	v_pk_mul_f32 v[86:87], v[4:5], v[40:41] op_sel:[0,1] op_sel_hi:[1,1]
	v_mov_b32_dpp v28, v58 quad_perm:[0,1,2,3] row_mask:0xf bank_mask:0xc
	v_add_f32_dpp v22, v22, v22 quad_perm:[2,3,0,1] row_mask:0xf bank_mask:0xf
	v_add_f32_dpp v23, v23, v23 quad_perm:[2,3,0,1] row_mask:0xf bank_mask:0xf
	v_pk_mul_f32 v[88:89], v[6:7], v[42:43] op_sel:[0,0] op_sel_hi:[1,0]
	v_pk_mul_f32 v[90:91], v[8:9], v[42:43] op_sel:[0,1] op_sel_hi:[1,1]
	v_add_f32_dpp v28, v28, v28 quad_perm:[1,0,3,2] row_mask:0xf bank_mask:0xf
	v_add_f32_dpp v22, v22, v22 row_half_mirror row_mask:0xf bank_mask:0xf
	v_add_f32_dpp v23, v23, v23 row_half_mirror row_mask:0xf bank_mask:0xf
	v_pk_fma_f32 v[84:85], v[48:49], v[56:57], v[84:85] op_sel:[0,0,0] op_sel_hi:[0,1,1]
	v_pk_fma_f32 v[86:87], v[48:49], v[56:57], v[86:87] op_sel:[1,0,0] op_sel_hi:[1,1,1]
	v_add_f32_dpp v28, v28, v28 quad_perm:[2,3,0,1] row_mask:0xf bank_mask:0xf
	v_add_f32_dpp v22, v22, v22 row_mirror row_mask:0xf bank_mask:0xf
	v_add_f32_dpp v23, v23, v23 row_mirror row_mask:0xf bank_mask:0xf
	v_pk_fma_f32 v[88:89], v[50:51], v[56:57], v[88:89] op_sel:[0,0,0] op_sel_hi:[0,1,1]
	v_pk_fma_f32 v[90:91], v[50:51], v[56:57], v[90:91] op_sel:[1,0,0] op_sel_hi:[1,1,1]
	v_cndmask_b32_e64 v32, v32, v28, s[10:11]
	v_pk_fma_f32 v[2:3], v[44:45], v[22:23], v[84:85] op_sel:[0,0,0] op_sel_hi:[0,1,1] neg_lo:[1,0,0] neg_hi:[1,0,0]
	v_pk_fma_f32 v[4:5], v[44:45], v[22:23], v[86:87] op_sel:[1,0,0] op_sel_hi:[1,1,1] neg_lo:[1,0,0] neg_hi:[1,0,0]
	v_pk_fma_f32 v[6:7], v[46:47], v[22:23], v[88:89] op_sel:[0,0,0] op_sel_hi:[0,1,1] neg_lo:[1,0,0] neg_hi:[1,0,0]
	v_pk_fma_f32 v[8:9], v[46:47], v[22:23], v[90:91] op_sel:[1,0,0] op_sel_hi:[1,1,1] neg_lo:[1,0,0] neg_hi:[1,0,0]
	s_waitcnt lgkmcnt(0)
	v_pk_mul_f32 v[22:23], v[2:3], v[60:61] op_sel:[0,0] op_sel_hi:[1,0]
	v_pk_mul_f32 v[28:29], v[2:3], v[52:53] op_sel:[0,0] op_sel_hi:[1,0]
	ds_read_b128 v[36:39], v20 offset:7168
	v_pk_fma_f32 v[22:23], v[4:5], v[60:61], v[22:23] op_sel:[0,1,0] op_sel_hi:[1,1,1]
	v_pk_fma_f32 v[28:29], v[4:5], v[52:53], v[28:29] op_sel:[0,1,0] op_sel_hi:[1,1,1]
	ds_read_b128 v[40:43], v20 offset:15360
	v_pk_fma_f32 v[22:23], v[6:7], v[62:63], v[22:23] op_sel:[0,0,0] op_sel_hi:[1,0,1]
	v_pk_fma_f32 v[28:29], v[6:7], v[54:55], v[28:29] op_sel:[0,0,0] op_sel_hi:[1,0,1]
	ds_read_b64 v[56:57], v21 offset:48128
	v_pk_fma_f32 v[22:23], v[8:9], v[62:63], v[22:23] op_sel:[0,1,0] op_sel_hi:[1,1,1]
	v_pk_fma_f32 v[28:29], v[8:9], v[54:55], v[28:29] op_sel:[0,1,0] op_sel_hi:[1,1,1]
	ds_read_b128 v[48:51], v20 offset:31744
	ds_read_b128 v[44:47], v20 offset:23552
	ds_read_b128 v[52:55], v20 offset:39936
	v_add_f32_dpp v24, v24, v24 row_ror:12 row_mask:0xf bank_mask:0x5
	v_add_f32_dpp v25, v25, v25 row_ror:4 row_mask:0xf bank_mask:0xa
	v_add_f32_dpp v22, v22, v22 quad_perm:[1,0,3,2] row_mask:0xf bank_mask:0xf
	v_add_f32_dpp v23, v23, v23 quad_perm:[1,0,3,2] row_mask:0xf bank_mask:0xf
	v_pk_mul_f32 v[84:85], v[2:3], v[64:65] op_sel:[0,0] op_sel_hi:[1,0]
	v_pk_mul_f32 v[86:87], v[4:5], v[64:65] op_sel:[0,1] op_sel_hi:[1,1]
	v_add_f32_dpp v26, v26, v26 row_ror:12 row_mask:0xf bank_mask:0x5
	v_add_f32_dpp v22, v22, v22 quad_perm:[2,3,0,1] row_mask:0xf bank_mask:0xf
	v_add_f32_dpp v23, v23, v23 quad_perm:[2,3,0,1] row_mask:0xf bank_mask:0xf
	v_pk_mul_f32 v[88:89], v[6:7], v[66:67] op_sel:[0,0] op_sel_hi:[1,0]
	v_pk_mul_f32 v[90:91], v[8:9], v[66:67] op_sel:[0,1] op_sel_hi:[1,1]
	v_add_f32_dpp v27, v27, v27 row_ror:4 row_mask:0xf bank_mask:0xa
	v_add_f32_dpp v22, v22, v22 row_half_mirror row_mask:0xf bank_mask:0xf
	v_add_f32_dpp v23, v23, v23 row_half_mirror row_mask:0xf bank_mask:0xf
	v_pk_fma_f32 v[84:85], v[72:73], v[80:81], v[84:85] op_sel:[0,0,0] op_sel_hi:[0,1,1]
	v_pk_fma_f32 v[86:87], v[72:73], v[80:81], v[86:87] op_sel:[1,0,0] op_sel_hi:[1,1,1]
	v_mov_b32_dpp v24, v25 quad_perm:[0,1,2,3] row_mask:0xf bank_mask:0xa
	v_add_f32_dpp v22, v22, v22 row_mirror row_mask:0xf bank_mask:0xf
	v_add_f32_dpp v23, v23, v23 row_mirror row_mask:0xf bank_mask:0xf
	v_pk_fma_f32 v[88:89], v[74:75], v[80:81], v[88:89] op_sel:[0,0,0] op_sel_hi:[0,1,1]
	v_pk_fma_f32 v[90:91], v[74:75], v[80:81], v[90:91] op_sel:[1,0,0] op_sel_hi:[1,1,1]
	v_mov_b32_dpp v26, v27 quad_perm:[0,1,2,3] row_mask:0xf bank_mask:0xa
	v_pk_fma_f32 v[2:3], v[68:69], v[22:23], v[84:85] op_sel:[0,0,0] op_sel_hi:[0,1,1] neg_lo:[1,0,0] neg_hi:[1,0,0]
	v_pk_fma_f32 v[4:5], v[68:69], v[22:23], v[86:87] op_sel:[1,0,0] op_sel_hi:[1,1,1] neg_lo:[1,0,0] neg_hi:[1,0,0]
	v_pk_fma_f32 v[6:7], v[70:71], v[22:23], v[88:89] op_sel:[0,0,0] op_sel_hi:[0,1,1] neg_lo:[1,0,0] neg_hi:[1,0,0]
	v_pk_fma_f32 v[8:9], v[70:71], v[22:23], v[90:91] op_sel:[1,0,0] op_sel_hi:[1,1,1] neg_lo:[1,0,0] neg_hi:[1,0,0]
	s_waitcnt lgkmcnt(0)
	v_pk_mul_f32 v[22:23], v[2:3], v[36:37] op_sel:[0,0] op_sel_hi:[1,0]
	v_pk_mul_f32 v[58:59], v[2:3], v[76:77] op_sel:[0,0] op_sel_hi:[1,0]
	ds_read_b128 v[60:63], v20 offset:7424
	v_pk_fma_f32 v[22:23], v[4:5], v[36:37], v[22:23] op_sel:[0,1,0] op_sel_hi:[1,1,1]
	v_pk_fma_f32 v[58:59], v[4:5], v[76:77], v[58:59] op_sel:[0,1,0] op_sel_hi:[1,1,1]
	ds_read_b128 v[64:67], v20 offset:15616
	v_pk_fma_f32 v[22:23], v[6:7], v[38:39], v[22:23] op_sel:[0,0,0] op_sel_hi:[1,0,1]
	v_pk_fma_f32 v[58:59], v[6:7], v[78:79], v[58:59] op_sel:[0,0,0] op_sel_hi:[1,0,1]
	ds_read_b64 v[80:81], v21 offset:48384
	v_pk_fma_f32 v[22:23], v[8:9], v[38:39], v[22:23] op_sel:[0,1,0] op_sel_hi:[1,1,1]
	v_pk_fma_f32 v[58:59], v[8:9], v[78:79], v[58:59] op_sel:[0,1,0] op_sel_hi:[1,1,1]
	ds_read_b128 v[72:75], v20 offset:32000
	ds_read_b128 v[68:71], v20 offset:23808
	ds_read_b128 v[76:79], v20 offset:40192
	v_add_f32_dpp v24, v24, v24 row_ror:8 row_mask:0xf bank_mask:0x3
	v_add_f32_dpp v26, v26, v26 row_ror:8 row_mask:0xf bank_mask:0xc
	v_add_f32_dpp v22, v22, v22 quad_perm:[1,0,3,2] row_mask:0xf bank_mask:0xf
	v_add_f32_dpp v23, v23, v23 quad_perm:[1,0,3,2] row_mask:0xf bank_mask:0xf
	v_pk_mul_f32 v[84:85], v[2:3], v[40:41] op_sel:[0,0] op_sel_hi:[1,0]
	v_pk_mul_f32 v[86:87], v[4:5], v[40:41] op_sel:[0,1] op_sel_hi:[1,1]
	v_mov_b32_dpp v24, v26 quad_perm:[0,1,2,3] row_mask:0xf bank_mask:0xc
	v_add_f32_dpp v22, v22, v22 quad_perm:[2,3,0,1] row_mask:0xf bank_mask:0xf
	v_add_f32_dpp v23, v23, v23 quad_perm:[2,3,0,1] row_mask:0xf bank_mask:0xf
	v_pk_mul_f32 v[88:89], v[6:7], v[42:43] op_sel:[0,0] op_sel_hi:[1,0]
	v_pk_mul_f32 v[90:91], v[8:9], v[42:43] op_sel:[0,1] op_sel_hi:[1,1]
	v_add_f32_dpp v24, v24, v24 quad_perm:[1,0,3,2] row_mask:0xf bank_mask:0xf
	v_add_f32_dpp v22, v22, v22 row_half_mirror row_mask:0xf bank_mask:0xf
	v_add_f32_dpp v23, v23, v23 row_half_mirror row_mask:0xf bank_mask:0xf
	v_pk_fma_f32 v[84:85], v[48:49], v[56:57], v[84:85] op_sel:[0,0,0] op_sel_hi:[0,1,1]
	v_pk_fma_f32 v[86:87], v[48:49], v[56:57], v[86:87] op_sel:[1,0,0] op_sel_hi:[1,1,1]
	v_add_f32_dpp v24, v24, v24 quad_perm:[2,3,0,1] row_mask:0xf bank_mask:0xf
	v_add_f32_dpp v22, v22, v22 row_mirror row_mask:0xf bank_mask:0xf
	v_add_f32_dpp v23, v23, v23 row_mirror row_mask:0xf bank_mask:0xf
	v_pk_fma_f32 v[88:89], v[50:51], v[56:57], v[88:89] op_sel:[0,0,0] op_sel_hi:[0,1,1]
	v_pk_fma_f32 v[90:91], v[50:51], v[56:57], v[90:91] op_sel:[1,0,0] op_sel_hi:[1,1,1]
	v_cndmask_b32_e64 v33, 0, v24, s[0:1]
	v_pk_fma_f32 v[2:3], v[44:45], v[22:23], v[84:85] op_sel:[0,0,0] op_sel_hi:[0,1,1] neg_lo:[1,0,0] neg_hi:[1,0,0]
	v_pk_fma_f32 v[4:5], v[44:45], v[22:23], v[86:87] op_sel:[1,0,0] op_sel_hi:[1,1,1] neg_lo:[1,0,0] neg_hi:[1,0,0]
	v_pk_fma_f32 v[6:7], v[46:47], v[22:23], v[88:89] op_sel:[0,0,0] op_sel_hi:[0,1,1] neg_lo:[1,0,0] neg_hi:[1,0,0]
	v_pk_fma_f32 v[8:9], v[46:47], v[22:23], v[90:91] op_sel:[1,0,0] op_sel_hi:[1,1,1] neg_lo:[1,0,0] neg_hi:[1,0,0]
	s_waitcnt lgkmcnt(0)
	v_pk_mul_f32 v[22:23], v[2:3], v[60:61] op_sel:[0,0] op_sel_hi:[1,0]
	v_pk_mul_f32 v[24:25], v[2:3], v[52:53] op_sel:[0,0] op_sel_hi:[1,0]
	ds_read_b128 v[36:39], v20 offset:7680
	v_pk_fma_f32 v[22:23], v[4:5], v[60:61], v[22:23] op_sel:[0,1,0] op_sel_hi:[1,1,1]
	v_pk_fma_f32 v[24:25], v[4:5], v[52:53], v[24:25] op_sel:[0,1,0] op_sel_hi:[1,1,1]
	ds_read_b128 v[40:43], v20 offset:15872
	v_pk_fma_f32 v[22:23], v[6:7], v[62:63], v[22:23] op_sel:[0,0,0] op_sel_hi:[1,0,1]
	v_pk_fma_f32 v[24:25], v[6:7], v[54:55], v[24:25] op_sel:[0,0,0] op_sel_hi:[1,0,1]
	ds_read_b64 v[56:57], v21 offset:48640
	v_pk_fma_f32 v[22:23], v[8:9], v[62:63], v[22:23] op_sel:[0,1,0] op_sel_hi:[1,1,1]
	v_pk_fma_f32 v[24:25], v[8:9], v[54:55], v[24:25] op_sel:[0,1,0] op_sel_hi:[1,1,1]
	ds_read_b128 v[48:51], v20 offset:32256
	ds_read_b128 v[44:47], v20 offset:24064
	ds_read_b128 v[52:55], v20 offset:40448
	v_add_f32_dpp v28, v28, v28 row_ror:12 row_mask:0xf bank_mask:0x5
	v_add_f32_dpp v29, v29, v29 row_ror:4 row_mask:0xf bank_mask:0xa
	v_add_f32_dpp v22, v22, v22 quad_perm:[1,0,3,2] row_mask:0xf bank_mask:0xf
	v_add_f32_dpp v23, v23, v23 quad_perm:[1,0,3,2] row_mask:0xf bank_mask:0xf
	v_pk_mul_f32 v[84:85], v[2:3], v[64:65] op_sel:[0,0] op_sel_hi:[1,0]
	v_pk_mul_f32 v[86:87], v[4:5], v[64:65] op_sel:[0,1] op_sel_hi:[1,1]
	v_add_f32_dpp v58, v58, v58 row_ror:12 row_mask:0xf bank_mask:0x5
	v_add_f32_dpp v22, v22, v22 quad_perm:[2,3,0,1] row_mask:0xf bank_mask:0xf
	v_add_f32_dpp v23, v23, v23 quad_perm:[2,3,0,1] row_mask:0xf bank_mask:0xf
	v_pk_mul_f32 v[88:89], v[6:7], v[66:67] op_sel:[0,0] op_sel_hi:[1,0]
	v_pk_mul_f32 v[90:91], v[8:9], v[66:67] op_sel:[0,1] op_sel_hi:[1,1]
	v_add_f32_dpp v59, v59, v59 row_ror:4 row_mask:0xf bank_mask:0xa
	v_add_f32_dpp v22, v22, v22 row_half_mirror row_mask:0xf bank_mask:0xf
	v_add_f32_dpp v23, v23, v23 row_half_mirror row_mask:0xf bank_mask:0xf
	v_pk_fma_f32 v[84:85], v[72:73], v[80:81], v[84:85] op_sel:[0,0,0] op_sel_hi:[0,1,1]
	v_pk_fma_f32 v[86:87], v[72:73], v[80:81], v[86:87] op_sel:[1,0,0] op_sel_hi:[1,1,1]
	v_mov_b32_dpp v28, v29 quad_perm:[0,1,2,3] row_mask:0xf bank_mask:0xa
	v_add_f32_dpp v22, v22, v22 row_mirror row_mask:0xf bank_mask:0xf
	v_add_f32_dpp v23, v23, v23 row_mirror row_mask:0xf bank_mask:0xf
	v_pk_fma_f32 v[88:89], v[74:75], v[80:81], v[88:89] op_sel:[0,0,0] op_sel_hi:[0,1,1]
	v_pk_fma_f32 v[90:91], v[74:75], v[80:81], v[90:91] op_sel:[1,0,0] op_sel_hi:[1,1,1]
	v_mov_b32_dpp v58, v59 quad_perm:[0,1,2,3] row_mask:0xf bank_mask:0xa
	v_pk_fma_f32 v[2:3], v[68:69], v[22:23], v[84:85] op_sel:[0,0,0] op_sel_hi:[0,1,1] neg_lo:[1,0,0] neg_hi:[1,0,0]
	v_pk_fma_f32 v[4:5], v[68:69], v[22:23], v[86:87] op_sel:[1,0,0] op_sel_hi:[1,1,1] neg_lo:[1,0,0] neg_hi:[1,0,0]
	v_pk_fma_f32 v[6:7], v[70:71], v[22:23], v[88:89] op_sel:[0,0,0] op_sel_hi:[0,1,1] neg_lo:[1,0,0] neg_hi:[1,0,0]
	v_pk_fma_f32 v[8:9], v[70:71], v[22:23], v[90:91] op_sel:[1,0,0] op_sel_hi:[1,1,1] neg_lo:[1,0,0] neg_hi:[1,0,0]
	s_waitcnt lgkmcnt(0)
	v_pk_mul_f32 v[22:23], v[2:3], v[36:37] op_sel:[0,0] op_sel_hi:[1,0]
	v_pk_mul_f32 v[26:27], v[2:3], v[76:77] op_sel:[0,0] op_sel_hi:[1,0]
	ds_read_b128 v[60:63], v20 offset:7936
	v_pk_fma_f32 v[22:23], v[4:5], v[36:37], v[22:23] op_sel:[0,1,0] op_sel_hi:[1,1,1]
	v_pk_fma_f32 v[26:27], v[4:5], v[76:77], v[26:27] op_sel:[0,1,0] op_sel_hi:[1,1,1]
	ds_read_b128 v[64:67], v20 offset:16128
	v_pk_fma_f32 v[22:23], v[6:7], v[38:39], v[22:23] op_sel:[0,0,0] op_sel_hi:[1,0,1]
	v_pk_fma_f32 v[26:27], v[6:7], v[78:79], v[26:27] op_sel:[0,0,0] op_sel_hi:[1,0,1]
	ds_read_b64 v[80:81], v21 offset:48896
	v_pk_fma_f32 v[22:23], v[8:9], v[38:39], v[22:23] op_sel:[0,1,0] op_sel_hi:[1,1,1]
	v_pk_fma_f32 v[26:27], v[8:9], v[78:79], v[26:27] op_sel:[0,1,0] op_sel_hi:[1,1,1]
	ds_read_b128 v[72:75], v20 offset:32512
	ds_read_b128 v[68:71], v20 offset:24320
	ds_read_b128 v[76:79], v20 offset:40704
	v_add_f32_dpp v28, v28, v28 row_ror:8 row_mask:0xf bank_mask:0x3
	v_add_f32_dpp v58, v58, v58 row_ror:8 row_mask:0xf bank_mask:0xc
	v_add_f32_dpp v22, v22, v22 quad_perm:[1,0,3,2] row_mask:0xf bank_mask:0xf
	v_add_f32_dpp v23, v23, v23 quad_perm:[1,0,3,2] row_mask:0xf bank_mask:0xf
	v_pk_mul_f32 v[84:85], v[2:3], v[40:41] op_sel:[0,0] op_sel_hi:[1,0]
	v_pk_mul_f32 v[86:87], v[4:5], v[40:41] op_sel:[0,1] op_sel_hi:[1,1]
	v_mov_b32_dpp v28, v58 quad_perm:[0,1,2,3] row_mask:0xf bank_mask:0xc
	v_add_f32_dpp v22, v22, v22 quad_perm:[2,3,0,1] row_mask:0xf bank_mask:0xf
	v_add_f32_dpp v23, v23, v23 quad_perm:[2,3,0,1] row_mask:0xf bank_mask:0xf
	v_pk_mul_f32 v[88:89], v[6:7], v[42:43] op_sel:[0,0] op_sel_hi:[1,0]
	v_pk_mul_f32 v[90:91], v[8:9], v[42:43] op_sel:[0,1] op_sel_hi:[1,1]
	v_add_f32_dpp v28, v28, v28 quad_perm:[1,0,3,2] row_mask:0xf bank_mask:0xf
	v_add_f32_dpp v22, v22, v22 row_half_mirror row_mask:0xf bank_mask:0xf
	v_add_f32_dpp v23, v23, v23 row_half_mirror row_mask:0xf bank_mask:0xf
	v_pk_fma_f32 v[84:85], v[48:49], v[56:57], v[84:85] op_sel:[0,0,0] op_sel_hi:[0,1,1]
	v_pk_fma_f32 v[86:87], v[48:49], v[56:57], v[86:87] op_sel:[1,0,0] op_sel_hi:[1,1,1]
	v_add_f32_dpp v28, v28, v28 quad_perm:[2,3,0,1] row_mask:0xf bank_mask:0xf
	v_add_f32_dpp v22, v22, v22 row_mirror row_mask:0xf bank_mask:0xf
	v_add_f32_dpp v23, v23, v23 row_mirror row_mask:0xf bank_mask:0xf
	v_pk_fma_f32 v[88:89], v[50:51], v[56:57], v[88:89] op_sel:[0,0,0] op_sel_hi:[0,1,1]
	v_pk_fma_f32 v[90:91], v[50:51], v[56:57], v[90:91] op_sel:[1,0,0] op_sel_hi:[1,1,1]
	v_cndmask_b32_e64 v33, v33, v28, s[6:7]
	v_pk_fma_f32 v[2:3], v[44:45], v[22:23], v[84:85] op_sel:[0,0,0] op_sel_hi:[0,1,1] neg_lo:[1,0,0] neg_hi:[1,0,0]
	v_pk_fma_f32 v[4:5], v[44:45], v[22:23], v[86:87] op_sel:[1,0,0] op_sel_hi:[1,1,1] neg_lo:[1,0,0] neg_hi:[1,0,0]
	v_pk_fma_f32 v[6:7], v[46:47], v[22:23], v[88:89] op_sel:[0,0,0] op_sel_hi:[0,1,1] neg_lo:[1,0,0] neg_hi:[1,0,0]
	v_pk_fma_f32 v[8:9], v[46:47], v[22:23], v[90:91] op_sel:[1,0,0] op_sel_hi:[1,1,1] neg_lo:[1,0,0] neg_hi:[1,0,0]
	s_waitcnt lgkmcnt(0)
	v_pk_mul_f32 v[22:23], v[2:3], v[60:61] op_sel:[0,0] op_sel_hi:[1,0]
	v_pk_mul_f32 v[28:29], v[2:3], v[52:53] op_sel:[0,0] op_sel_hi:[1,0]
	v_pk_fma_f32 v[22:23], v[4:5], v[60:61], v[22:23] op_sel:[0,1,0] op_sel_hi:[1,1,1]
	v_pk_fma_f32 v[28:29], v[4:5], v[52:53], v[28:29] op_sel:[0,1,0] op_sel_hi:[1,1,1]
	v_pk_fma_f32 v[22:23], v[6:7], v[62:63], v[22:23] op_sel:[0,0,0] op_sel_hi:[1,0,1]
	v_pk_fma_f32 v[28:29], v[6:7], v[54:55], v[28:29] op_sel:[0,0,0] op_sel_hi:[1,0,1]
	v_pk_fma_f32 v[22:23], v[8:9], v[62:63], v[22:23] op_sel:[0,1,0] op_sel_hi:[1,1,1]
	v_pk_fma_f32 v[28:29], v[8:9], v[54:55], v[28:29] op_sel:[0,1,0] op_sel_hi:[1,1,1]
	v_add_f32_dpp v24, v24, v24 row_ror:12 row_mask:0xf bank_mask:0x5
	v_add_f32_dpp v25, v25, v25 row_ror:4 row_mask:0xf bank_mask:0xa
	v_add_f32_dpp v22, v22, v22 quad_perm:[1,0,3,2] row_mask:0xf bank_mask:0xf
	v_add_f32_dpp v23, v23, v23 quad_perm:[1,0,3,2] row_mask:0xf bank_mask:0xf
	v_pk_mul_f32 v[84:85], v[2:3], v[64:65] op_sel:[0,0] op_sel_hi:[1,0]
	v_pk_mul_f32 v[86:87], v[4:5], v[64:65] op_sel:[0,1] op_sel_hi:[1,1]
	v_add_f32_dpp v26, v26, v26 row_ror:12 row_mask:0xf bank_mask:0x5
	v_add_f32_dpp v22, v22, v22 quad_perm:[2,3,0,1] row_mask:0xf bank_mask:0xf
	v_add_f32_dpp v23, v23, v23 quad_perm:[2,3,0,1] row_mask:0xf bank_mask:0xf
	v_pk_mul_f32 v[88:89], v[6:7], v[66:67] op_sel:[0,0] op_sel_hi:[1,0]
	v_pk_mul_f32 v[90:91], v[8:9], v[66:67] op_sel:[0,1] op_sel_hi:[1,1]
	v_add_f32_dpp v27, v27, v27 row_ror:4 row_mask:0xf bank_mask:0xa
	v_add_f32_dpp v22, v22, v22 row_half_mirror row_mask:0xf bank_mask:0xf
	v_add_f32_dpp v23, v23, v23 row_half_mirror row_mask:0xf bank_mask:0xf
	v_pk_fma_f32 v[84:85], v[72:73], v[80:81], v[84:85] op_sel:[0,0,0] op_sel_hi:[0,1,1]
	v_pk_fma_f32 v[86:87], v[72:73], v[80:81], v[86:87] op_sel:[1,0,0] op_sel_hi:[1,1,1]
	v_mov_b32_dpp v24, v25 quad_perm:[0,1,2,3] row_mask:0xf bank_mask:0xa
	v_add_f32_dpp v22, v22, v22 row_mirror row_mask:0xf bank_mask:0xf
	v_add_f32_dpp v23, v23, v23 row_mirror row_mask:0xf bank_mask:0xf
	v_pk_fma_f32 v[88:89], v[74:75], v[80:81], v[88:89] op_sel:[0,0,0] op_sel_hi:[0,1,1]
	v_pk_fma_f32 v[90:91], v[74:75], v[80:81], v[90:91] op_sel:[1,0,0] op_sel_hi:[1,1,1]
	v_mov_b32_dpp v26, v27 quad_perm:[0,1,2,3] row_mask:0xf bank_mask:0xa
	v_pk_fma_f32 v[2:3], v[68:69], v[22:23], v[84:85] op_sel:[0,0,0] op_sel_hi:[0,1,1] neg_lo:[1,0,0] neg_hi:[1,0,0]
	v_pk_fma_f32 v[4:5], v[68:69], v[22:23], v[86:87] op_sel:[1,0,0] op_sel_hi:[1,1,1] neg_lo:[1,0,0] neg_hi:[1,0,0]
	v_pk_fma_f32 v[6:7], v[70:71], v[22:23], v[88:89] op_sel:[0,0,0] op_sel_hi:[0,1,1] neg_lo:[1,0,0] neg_hi:[1,0,0]
	v_pk_fma_f32 v[8:9], v[70:71], v[22:23], v[90:91] op_sel:[1,0,0] op_sel_hi:[1,1,1] neg_lo:[1,0,0] neg_hi:[1,0,0]
	s_waitcnt lgkmcnt(0)
	v_pk_mul_f32 v[58:59], v[2:3], v[76:77] op_sel:[0,0] op_sel_hi:[1,0]
	v_pk_fma_f32 v[58:59], v[4:5], v[76:77], v[58:59] op_sel:[0,1,0] op_sel_hi:[1,1,1]
	v_pk_fma_f32 v[58:59], v[6:7], v[78:79], v[58:59] op_sel:[0,0,0] op_sel_hi:[1,0,1]
	v_pk_fma_f32 v[58:59], v[8:9], v[78:79], v[58:59] op_sel:[0,1,0] op_sel_hi:[1,1,1]
	v_add_f32_dpp v24, v24, v24 row_ror:8 row_mask:0xf bank_mask:0x3
	v_add_f32_dpp v26, v26, v26 row_ror:8 row_mask:0xf bank_mask:0xc
	s_nop 1
	v_mov_b32_dpp v24, v26 quad_perm:[0,1,2,3] row_mask:0xf bank_mask:0xc
	s_nop 1
	v_add_f32_dpp v24, v24, v24 quad_perm:[1,0,3,2] row_mask:0xf bank_mask:0xf
	s_nop 1
	v_add_f32_dpp v24, v24, v24 quad_perm:[2,3,0,1] row_mask:0xf bank_mask:0xf
	v_cndmask_b32_e64 v33, v33, v24, s[8:9]
	v_add_f32_dpp v28, v28, v28 row_ror:12 row_mask:0xf bank_mask:0x5
	v_add_f32_dpp v29, v29, v29 row_ror:4 row_mask:0xf bank_mask:0xa
	v_add_f32_dpp v58, v58, v58 row_ror:12 row_mask:0xf bank_mask:0x5
	v_add_f32_dpp v59, v59, v59 row_ror:4 row_mask:0xf bank_mask:0xa
	v_mov_b32_dpp v28, v29 quad_perm:[0,1,2,3] row_mask:0xf bank_mask:0xa
	s_nop 0
	v_mov_b32_dpp v58, v59 quad_perm:[0,1,2,3] row_mask:0xf bank_mask:0xa
	v_add_f32_dpp v28, v28, v28 row_ror:8 row_mask:0xf bank_mask:0x3
	s_nop 0
	v_add_f32_dpp v58, v58, v58 row_ror:8 row_mask:0xf bank_mask:0xc
	s_nop 1
	v_mov_b32_dpp v28, v58 quad_perm:[0,1,2,3] row_mask:0xf bank_mask:0xc
	s_nop 1
	v_add_f32_dpp v28, v28, v28 quad_perm:[1,0,3,2] row_mask:0xf bank_mask:0xf
	s_nop 1
	v_add_f32_dpp v28, v28, v28 quad_perm:[2,3,0,1] row_mask:0xf bank_mask:0xf
	v_cndmask_b32_e64 v33, v33, v28, s[10:11]
	v_lshl_add_u32 v35, s23, 12, v11
	s_add_i32 s22, s22, 1
	ds_write2st64_b32 v35, v30, v31 offset1:4
	ds_write2st64_b32 v35, v32, v33 offset0:8 offset1:12
	s_cmp_eq_u32 s22, 64
	s_waitcnt lgkmcnt(0)
	s_barrier
	s_cbranch_scc0 .LBB0_1750
	s_setprio 0
	s_lshl_b32 s0, s18, 4
	s_or_b32 s0, s0, s26
	s_ashr_i32 s1, s0, 31
	s_lshl_b64 s[0:1], s[0:1], 6
	s_lshl_b32 s2, s27, 5
	s_or_b32 s0, s0, s2
	v_or_b32_e32 v12, s0, v1
	v_mov_b32_e32 v13, s1
	v_lshlrev_b64 v[12:13], 8, v[12:13]
	v_lshl_add_u64 v[12:13], s[82:83], 0, v[12:13]
	v_mov_b32_e32 v11, 0
	v_lshl_add_u64 v[10:11], v[12:13], 0, v[10:11]
	s_mov_b64 s[0:1], 0x4100000
	v_lshl_add_u64 v[12:13], v[10:11], 0, s[0:1]
	v_add_co_u32_e32 v10, vcc, 0x4100000, v10
	s_nop 1
	v_addc_co_u32_e32 v11, vcc, 0, v11, vcc
	v_mov_b32_e32 v14, v2
	v_mov_b32_e32 v15, v4
	v_mov_b32_e32 v16, v6
	v_mov_b32_e32 v17, v8
	v_mov_b32_e32 v18, v3
	v_mov_b32_e32 v19, v5
	v_mov_b32_e32 v20, v7
	v_mov_b32_e32 v21, v9
	global_store_dwordx4 v[10:11], v[14:17], off
	global_store_dwordx4 v[12:13], v[18:21], off offset:256
